# kv-projection task: loop-invariant rms-norm gain vectors loaded once before the task loop (were re-loaded per token block in 8 serialised load-wait-use steps); weight fragment addresses as base + imme
# speedup vs baseline: 1.0044x; 1.0044x over previous
; __device__ __forceinline__ unsigned cvt_pk_bf16(float lo, float hi) { unsigned r; asm volatile("v_cvt_pk_bf16_f32 %0, %1, %2" : "=v"(r) : "v"(lo), "v"(hi)); return r; }
; __device__ __forceinline__ float bflo(unsigned w) { return __uint_as_float(w << 16); }
; __device__ __forceinline__ float bfhi(unsigned w) { return __uint_as_float(w & 0xffff0000u); }
; __device__ __forceinline__ void kvproj_task(int t, int l, const float* kvnorm, const float* kgain, const bf16_t* P, const bf16_t* WUKV, bf16_t* KB, bf16_t* VT, int fr, int fq) {
;     const int h = t & 3, row0 = (t >> 2) * 32 + fr; const bool isc = row0 >= ML;
;     bf16x8 bfr[2][4]; f32x4 kr[2][2]; float skr[2];
; #pragma unroll
;     for (int tb = 0; tb < 2; ++tb) { const int row = row0 + tb * 16; float ss = 0.f; u32x4 raw[4];
; #pragma unroll
;         for (int ks = 0; ks < 4; ++ks) { raw[ks] = ld8(P + (size_t)row * INP + ks * 32 + fq * 8); UNPK8(raw[ks], x);
;             ss += (x[0] * x[0] + x[1] * x[1]) + (x[2] * x[2] + x[3] * x[3]) + (x[4] * x[4] + x[5] * x[5]) + (x[6] * x[6] + x[7] * x[7]); }
; #pragma unroll
;         for (int cbr = 0; cbr < 2; ++cbr) { const u32x2 w = ld4(P + (size_t)row * INP + OFF_KROPE + cbr * 16 + fq * 4); kr[tb][cbr] = (f32x4){bflo(w.x), bfhi(w.x), bflo(w.y), bfhi(w.y)}; }
;         ss += __shfl_xor(ss, 16); ss += __shfl_xor(ss, 32);
;         const float rinv = rsqrtf(ss * (1.f / 128.f) + EPS);
; #pragma unroll
;         for (int ks = 0; ks < 4; ++ks) { const float* gp = kvnorm + l * 128 + ks * 32 + fq * 8; const f32x4 g0 = *(const f32x4*)gp, g1 = *(const f32x4*)(gp + 4); UNPK8(raw[ks], x); u32x4 o;
;             o.x = cvt_pk_bf16(x[0] * rinv * g0[0], x[1] * rinv * g0[1]); o.y = cvt_pk_bf16(x[2] * rinv * g0[2], x[3] * rinv * g0[3]);
;             o.z = cvt_pk_bf16(x[4] * rinv * g1[0], x[5] * rinv * g1[1]); o.w = cvt_pk_bf16(x[6] * rinv * g1[2], x[7] * rinv * g1[3]);
;             bfr[tb][ks] = asfrag(o); }
;         skr[tb] = (kr[tb][0][0] * kr[tb][0][0] + kr[tb][0][1] * kr[tb][0][1]) + (kr[tb][0][2] * kr[tb][0][2] + kr[tb][0][3] * kr[tb][0][3]) + (kr[tb][1][0] * kr[tb][1][0] + kr[tb][1][1] * kr[tb][1][1]) + (kr[tb][1][2] * kr[tb][1][2] + kr[tb][1][3] * kr[tb][1][3]); }
;     const bf16_t* wk0 = WUKV + ((size_t)l * 512 + h * 128 + fr) * 128 + fq * 8;
;     bf16x8 wf[2][4];
; #pragma unroll
;     for (int ks = 0; ks < 4; ++ks) wf[0][ks] = asfrag(ld8(wk0 + ks * 32));
.LBB0_419:
	s_mov_b64 s[42:43], s[72:73]
	v_mov_b32 v0, v194
	v_readlane_b32 s6, v253, 4
	v_readfirstlane_b32 s20, v0
	s_ashr_i32 s1, s20, 6
	v_readlane_b32 s7, v253, 5
	s_add_i32 s21, s1, s69
	v_and_b32_e32 v97, 15, v0
	v_bfe_u32 v214, v0, 4, 2
	s_mov_b64 s[4:5], -1
	s_and_b64 vcc, exec, s[6:7]
	s_cbranch_vccz .LBB0_424
	s_cmpk_gt_i32 s21, 0x8ff
	s_movk_i32 s14, 0xc0
	s_mov_b32 s15, 0x12000
	s_mov_b32 s18, 0x14000
	s_movk_i32 s19, 0x1000
	s_movk_i32 s23, 0x3000
	s_mov_b32 s24, 0x13000
	s_mov_b32 s25, 0x15000
	s_mov_b32 s26, 0x24000
	s_mov_b32 s27, 0x25000
	s_mov_b32 s44, 0x26000
	s_mov_b32 s45, 0x27000
	s_mov_b32 s46, 0x36000
	s_mov_b32 s48, 0x37000
	s_mov_b32 s51, 0x38000
	s_mov_b32 s52, 0x39000
	s_cbranch_scc1 .LBB0_423
	v_and_b32_e32 v5, 64, v199
	v_xor_b32_e32 v4, 16, v199
	v_add_u32_e32 v5, 64, v5
	v_cmp_lt_i32_e32 vcc, v4, v5
	v_readlane_b32 s6, v254, 27
	v_readlane_b32 s7, v254, 28
	v_cndmask_b32_e32 v4, v199, v4, vcc
	v_lshlrev_b32_e32 v215, 2, v4
	v_xor_b32_e32 v4, 32, v199
	v_cmp_lt_i32_e32 vcc, v4, v5
	v_mov_b32_e32 v5, v1
	s_add_u32 s4, s42, 0x8eb8000
	v_cndmask_b32_e32 v4, v199, v4, vcc
	v_lshlrev_b32_e32 v216, 2, v4
	v_lshlrev_b32_e32 v4, 5, v214
	v_lshl_add_u64 v[98:99], s[6:7], 0, v[4:5]
	v_readlane_b32 s6, v254, 30
	s_addc_u32 s5, s43, 0
	v_lshlrev_b32_e32 v0, 3, v214
	v_lshlrev_b32_e32 v2, 4, v214
	v_mov_b32_e32 v3, v1
	v_readlane_b32 s7, v254, 31
	v_lshl_add_u64 v[94:95], s[4:5], 0, v[2:3]
	v_lshlrev_b32_e32 v96, 2, v214
	v_lshl_add_u64 v[4:5], s[42:43], 0, v[2:3]
	v_lshl_add_u64 v[100:101], s[6:7], 0, v[2:3]
	v_lshl_add_u64 v[2:3], s[42:43], 0, v[0:1]
	s_mov_b64 s[6:7], 0x7838000
	v_lshl_add_u64 v[102:103], v[2:3], 0, s[6:7]
	v_and_b32_e32 v2, 4, v96
	v_cvt_f32_ubyte0_e32 v3, v2
	v_mul_f32_e32 v3, 0xbfd49a78, v3
	v_exp_f32_e32 v217, v3
	v_or_b32_e32 v3, 1, v2
	v_cvt_f32_ubyte0_e32 v3, v3
	s_add_u32 s40, s42, 0x85b8000
	v_mul_f32_e32 v3, 0xbfd49a78, v3
	s_addc_u32 s41, s43, 0
	v_exp_f32_e32 v218, v3
	v_or_b32_e32 v3, 2, v2
	v_or_b32_e32 v2, 3, v2
	s_bfe_u32 s22, s20, 0x20006
	v_cvt_f32_ubyte0_e32 v2, v2
	s_lshl_b32 s6, s22, 7
	v_readlane_b32 s7, v254, 29
	v_cvt_f32_ubyte0_e32 v3, v3
	v_mul_f32_e32 v2, 0xbfd49a78, v2
	s_or_b32 s6, s7, s6
	v_mul_f32_e32 v3, 0xbfd49a78, v3
	v_exp_f32_e32 v220, v2
	v_or_b32_e32 v2, s6, v97
	v_exp_f32_e32 v219, v3
	v_lshlrev_b32_e32 v2, 7, v2
	v_mov_b32_e32 v3, v1
	v_lshl_add_u64 v[2:3], v[2:3], 1, v[4:5]
	s_mov_b64 s[6:7], 0x2260000
	v_lshl_add_u64 v[104:105], v[2:3], 0, s[6:7]
	s_mov_b64 s[6:7], 0x2261000
	v_lshl_add_u64 v[106:107], v[2:3], 0, s[6:7]
	s_mov_b64 s[6:7], 0x2261040
	v_lshl_add_u64 v[108:109], v[2:3], 0, s[6:7]
	s_mov_b64 s[6:7], 0x2261080
	v_lshl_add_u64 v[110:111], v[2:3], 0, s[6:7]
	s_mov_b64 s[6:7], 0x22610c0
	v_lshl_add_u64 v[112:113], v[2:3], 0, s[6:7]
	s_mov_b64 s[6:7], 0x2262000
	v_lshl_add_u64 v[114:115], v[2:3], 0, s[6:7]
	s_mov_b64 s[6:7], 0x2262040
	v_lshl_add_u64 v[116:117], v[2:3], 0, s[6:7]
	s_mov_b64 s[6:7], 0x2262080
	v_lshl_add_u64 v[118:119], v[2:3], 0, s[6:7]
	s_mov_b64 s[6:7], 0x22620c0
	v_lshl_add_u64 v[120:121], v[2:3], 0, s[6:7]
	s_mov_b64 s[6:7], 0x2263000
	v_lshl_add_u64 v[122:123], v[2:3], 0, s[6:7]
	s_mov_b64 s[6:7], 0x2263040
	v_lshl_add_u64 v[124:125], v[2:3], 0, s[6:7]
	s_mov_b64 s[6:7], 0x2263080
	v_lshl_add_u64 v[126:127], v[2:3], 0, s[6:7]
	s_mov_b64 s[6:7], 0x22630c0
	v_lshl_add_u64 v[128:129], v[2:3], 0, s[6:7]
	s_mov_b64 s[6:7], 0x2264000
	v_lshl_add_u64 v[130:131], v[2:3], 0, s[6:7]
	s_mov_b64 s[6:7], 0x2264040
	v_lshl_add_u64 v[132:133], v[2:3], 0, s[6:7]
	s_mov_b64 s[6:7], 0x2264080
	v_lshl_add_u64 v[134:135], v[2:3], 0, s[6:7]
	s_mov_b64 s[6:7], 0x22640c0
	v_lshl_add_u64 v[136:137], v[2:3], 0, s[6:7]
	s_mov_b64 s[6:7], 0x2265000
	v_lshl_add_u64 v[138:139], v[2:3], 0, s[6:7]
	s_mov_b64 s[6:7], 0x2265040
	v_lshl_add_u64 v[140:141], v[2:3], 0, s[6:7]
	s_mov_b64 s[6:7], 0x2265080
	v_lshl_add_u64 v[142:143], v[2:3], 0, s[6:7]
	s_mov_b64 s[6:7], 0x22650c0
	v_lshl_add_u64 v[144:145], v[2:3], 0, s[6:7]
	s_mov_b64 s[6:7], 0x2266000
	v_lshl_add_u64 v[146:147], v[2:3], 0, s[6:7]
	s_mov_b64 s[6:7], 0x2266040
	v_lshl_add_u64 v[148:149], v[2:3], 0, s[6:7]
	s_mov_b64 s[6:7], 0x2266080
	v_lshl_add_u64 v[156:157], v[2:3], 0, s[6:7]
	s_mov_b64 s[6:7], 0x22660c0
	v_lshl_add_u64 v[158:159], v[2:3], 0, s[6:7]
	s_mov_b64 s[6:7], 0x2267000
	v_lshl_add_u64 v[160:161], v[2:3], 0, s[6:7]
	s_mov_b64 s[6:7], 0x2267040
	v_lshl_add_u64 v[162:163], v[2:3], 0, s[6:7]
	s_mov_b64 s[6:7], 0x2267080
	v_lshl_add_u64 v[164:165], v[2:3], 0, s[6:7]
	s_mov_b64 s[6:7], 0x22670c0
	v_lshl_add_u64 v[168:169], s[4:5], 0, v[0:1]
	s_lshl_b32 s1, s1, 3
	v_readlane_b32 s4, v253, 10
	v_cmp_gt_u32_e64 s[36:37], 2, v214
	v_lshl_add_u64 v[166:167], v[2:3], 0, s[6:7]
	s_add_i32 s4, s4, s1
	s_mov_b32 s5, s21
	global_load_dwordx4 v[108:111], v[98:99], off
	global_load_dwordx4 v[116:119], v[98:99], off offset:16
	global_load_dwordx4 v[124:127], v[98:99], off offset:128
	global_load_dwordx4 v[132:135], v[98:99], off offset:144
	global_load_dwordx4 v[140:143], v[98:99], off offset:256
	global_load_dwordx4 v[162:165], v[98:99], off offset:272
	global_load_dwordx4 v[156:159], v[98:99], off offset:384
	global_load_dwordx2 v[112:113], v[98:99], off offset:400
	global_load_dwordx2 v[120:121], v[98:99], off offset:408
	s_nop 0
	s_nop 0
	s_nop 0
	s_nop 0
	s_nop 0
	s_nop 0
	s_nop 0
	s_nop 0
	s_nop 0
	s_nop 0
	s_nop 0
	s_nop 0
	s_nop 0
	s_nop 0
; __device__ __forceinline__ unsigned cvt_pk_bf16(float lo, float hi) { unsigned r; asm volatile("v_cvt_pk_bf16_f32 %0, %1, %2" : "=v"(r) : "v"(lo), "v"(hi)); return r; }
; __device__ __forceinline__ float bflo(unsigned w) { return __uint_as_float(w << 16); }
; __device__ __forceinline__ float bfhi(unsigned w) { return __uint_as_float(w & 0xffff0000u); }
; #define UNPK8(VV_, XX_) float XX_[8] = {bflo((VV_).x), bfhi((VV_).x), bflo((VV_).y), bfhi((VV_).y), bflo((VV_).z), bfhi((VV_).z), bflo((VV_).w), bfhi((VV_).w)}
; __device__ __forceinline__ void kvproj_task(int t, int l, const float* kvnorm, const float* kgain, const bf16_t* P, const bf16_t* WUKV, bf16_t* KB, bf16_t* VT, int fr, int fq) {
;     ...
;     for (int tb = 0; tb < 2; ++tb) { const int row = row0 + tb * 16; float ss = 0.f; u32x4 raw[4];
; #pragma unroll
;         for (int ks = 0; ks < 4; ++ks) { raw[ks] = ld8(P + (size_t)row * INP + ks * 32 + fq * 8); UNPK8(raw[ks], x);
;             ss += (x[0] * x[0] + x[1] * x[1]) + (x[2] * x[2] + x[3] * x[3]) + (x[4] * x[4] + x[5] * x[5]) + (x[6] * x[6] + x[7] * x[7]); }
; #pragma unroll
;         for (int cbr = 0; cbr < 2; ++cbr) { const u32x2 w = ld4(P + (size_t)row * INP + OFF_KROPE + cbr * 16 + fq * 4); kr[tb][cbr] = (f32x4){bflo(w.x), bfhi(w.x), bflo(w.y), bfhi(w.y)}; }
;         ss += __shfl_xor(ss, 16); ss += __shfl_xor(ss, 32);
;         const float rinv = rsqrtf(ss * (1.f / 128.f) + EPS);
; #pragma unroll
;         for (int ks = 0; ks < 4; ++ks) { const float* gp = kvnorm + l * 128 + ks * 32 + fq * 8; const f32x4 g0 = *(const f32x4*)gp, g1 = *(const f32x4*)(gp + 4); UNPK8(raw[ks], x); u32x4 o;
;             o.x = cvt_pk_bf16(x[0] * rinv * g0[0], x[1] * rinv * g0[1]); o.y = cvt_pk_bf16(x[2] * rinv * g0[2], x[3] * rinv * g0[3]);
;             o.z = cvt_pk_bf16(x[4] * rinv * g1[0], x[5] * rinv * g1[1]); o.w = cvt_pk_bf16(x[6] * rinv * g1[2], x[7] * rinv * g1[3]);
;             bfr[tb][ks] = asfrag(o); }
.LBB0_422:
	s_and_b32 s1, s4, 0xffffffe0
	v_or_b32_e32 v171, s1, v97
	v_mad_i64_i32 v[6:7], s[6:7], v171, s84, v[94:95]
	flat_load_dwordx4 v[14:17], v[6:7]
	flat_load_dwordx4 v[2:5], v[6:7] offset:64
	flat_load_dwordx4 v[40:43], v[6:7] offset:128
	flat_load_dwordx4 v[50:53], v[6:7] offset:192
	v_or_b32_e32 v173, 16, v171
	s_add_i32 s5, s5, s60
	s_add_i32 s4, s4, s75
	s_cmpk_gt_i32 s5, 0x8ff
	s_waitcnt vmcnt(0) lgkmcnt(0)
	v_and_b32_e32 v37, 0xffff0000, v15
	v_and_b32_e32 v25, 0xffff0000, v3
	v_and_b32_e32 v24, 0xffff0000, v2
	v_lshlrev_b32_e32 v27, 16, v3
	v_lshlrev_b32_e32 v26, 16, v2
	v_pk_mul_f32 v[2:3], v[24:25], v[24:25]
	v_and_b32_e32 v21, 0xffff0000, v5
	v_and_b32_e32 v20, 0xffff0000, v4
	v_pk_fma_f32 v[2:3], v[26:27], v[26:27], v[2:3]
	v_lshlrev_b32_e32 v23, 16, v5
	v_lshlrev_b32_e32 v22, 16, v4
	v_pk_mul_f32 v[4:5], v[20:21], v[20:21]
	v_pk_add_f32 v[2:3], v[2:3], v[2:3] op_sel:[0,1] op_sel_hi:[1,0]
	v_pk_fma_f32 v[34:35], v[22:23], v[22:23], v[4:5]
	v_and_b32_e32 v39, 0xffff0000, v14
	v_pk_add_f32 v[44:45], v[34:35], v[2:3]
	v_mad_i64_i32 v[2:3], s[6:7], v171, s84, v[168:169]
	flat_load_dwordx2 v[4:5], v[2:3] offset:256
	s_nop 0
	flat_load_dwordx2 v[2:3], v[2:3] offset:288
	v_and_b32_e32 v38, 0xffff0000, v16
	v_lshlrev_b32_e32 v36, 16, v15
	v_mul_f32_e32 v0, v37, v37
	v_lshlrev_b32_e32 v18, 16, v40
	v_and_b32_e32 v19, 0xffff0000, v40
	v_lshlrev_b32_e32 v8, 16, v41
	v_and_b32_e32 v9, 0xffff0000, v41
	v_lshlrev_b32_e32 v41, 16, v14
	v_lshlrev_b32_e32 v40, 16, v16
	v_pk_mul_f32 v[14:15], v[38:39], v[38:39]
	v_pk_fma_f32 v[28:29], v[36:37], v[36:37], v[0:1] op_sel_hi:[1,1,0]
	v_lshlrev_b32_e32 v7, 16, v53
	v_pk_fma_f32 v[14:15], v[40:41], v[40:41], v[14:15]
	v_mul_f32_e32 v6, v19, v19
	v_lshlrev_b32_e32 v32, 16, v17
	v_and_b32_e32 v33, 0xffff0000, v17
	v_lshlrev_b32_e32 v48, 16, v51
	v_and_b32_e32 v47, 0xffff0000, v51
	v_pk_add_f32 v[16:17], v[14:15], v[28:29] op_sel:[1,0] op_sel_hi:[0,1]
	v_lshlrev_b32_e32 v31, 16, v50
	v_and_b32_e32 v29, 0xffff0000, v50
	v_pk_fma_f32 v[50:51], v[18:19], v[18:19], v[6:7] op_sel_hi:[1,1,0]
	v_mul_f32_e32 v6, v9, v9
	v_and_b32_e32 v0, 0xffff0000, v53
	v_mul_f32_e32 v46, v48, v48
	v_mul_f32_e32 v49, v47, v47
	v_pk_add_f32 v[54:55], v[14:15], v[16:17]
	v_and_b32_e32 v28, 0xffff0000, v42
	v_pk_mov_b32 v[14:15], v[42:43], v[52:53] op_sel:[1,0]
	v_lshlrev_b32_e32 v17, 16, v52
	v_pk_fma_f32 v[52:53], v[8:9], v[8:9], v[6:7] op_sel_hi:[1,1,0]
	v_lshlrev_b32_e32 v30, 16, v42
	v_lshlrev_b32_e32 v16, 16, v43
	v_pk_mul_f32 v[42:43], v[28:29], v[28:29]
	v_mov_b32_e32 v51, v46
	v_mov_b32_e32 v53, v49
	v_and_b32_e32 v15, 0xffff0000, v15
	v_and_b32_e32 v14, 0xffff0000, v14
	v_pk_fma_f32 v[42:43], v[30:31], v[30:31], v[42:43]
	v_pk_add_f32 v[50:51], v[50:51], v[52:53]
	v_mul_f32_e32 v6, v33, v33
	v_pk_add_f32 v[42:43], v[42:43], v[50:51]
	v_pk_mul_f32 v[50:51], v[14:15], v[14:15]
	v_mov_b32_e32 v52, v54
	v_pk_fma_f32 v[50:51], v[16:17], v[16:17], v[50:51]
	v_mov_b32_e32 v53, v7
	v_pk_add_f32 v[42:43], v[50:51], v[42:43]
	v_pk_fma_f32 v[50:51], v[32:33], v[32:33], v[6:7] op_sel_hi:[1,1,0]
	v_mul_f32_e32 v56, v0, v0
	v_mov_b32_e32 v6, v50
	v_pk_add_f32 v[50:51], v[50:51], v[54:55]
	v_pk_mul_f32 v[52:53], v[6:7], v[52:53]
	v_pk_add_f32 v[34:35], v[34:35], v[44:45] op_sel:[1,0] op_sel_hi:[0,1]
	v_mov_b32_e32 v51, v53
	v_mov_b32_e32 v35, v56
	v_pk_add_f32 v[34:35], v[50:51], v[34:35]
	s_waitcnt vmcnt(0) lgkmcnt(0)
	v_and_b32_e32 v189, 0xffff0000, v5
	v_pk_add_f32 v[34:35], v[34:35], v[42:43]
	s_nop 0
	s_nop 0
	s_nop 0
	s_nop 0
	v_lshlrev_b32_e32 v174, 16, v3
	v_and_b32_e32 v176, 0xffff0000, v3
	v_add_f32_e32 v3, v34, v35
	ds_bpermute_b32 v6, v215, v3
	v_and_b32_e32 v188, 0xffff0000, v4
	v_lshlrev_b32_e32 v187, 16, v5
	v_lshlrev_b32_e32 v186, 16, v4
	v_pk_mul_f32 v[4:5], v[188:189], v[188:189]
	s_waitcnt lgkmcnt(0)
	v_add_f32_e32 v3, v3, v6
	ds_bpermute_b32 v6, v216, v3
	v_pk_fma_f32 v[190:191], v[186:187], v[186:187], v[4:5]
	v_lshlrev_b32_e32 v184, 16, v2
	v_and_b32_e32 v185, 0xffff0000, v2
	s_waitcnt lgkmcnt(0)
	v_add_f32_e32 v3, v3, v6
	v_fmamk_f32 v3, v3, 0x3c000000, v197
	v_cmp_gt_f32_e32 vcc, s47, v3
	v_mul_f32_e32 v6, 0x4b800000, v3
	s_nop 0
	v_cndmask_b32_e32 v3, v3, v6, vcc
	v_rsq_f32_e32 v3, v3
	s_nop 0
	v_mul_f32_e32 v6, 0x45800000, v3
	v_cndmask_b32_e32 v3, v3, v6, vcc
	v_mul_f32_e32 v6, v3, v41
	v_mul_f32_e32 v34, v3, v39
	v_mul_f32_e32 v35, v3, v37
	v_mul_f32_e32 v24, v3, v24
	v_mul_f32_e32 v20, v3, v20
	v_mul_f32_e32 v0, v3, v0
	s_waitcnt vmcnt(0)
	v_mul_f32_e32 v6, v108, v6
	v_mul_f32_e32 v34, v109, v34
	v_cvt_pk_bf16_f32 v34, v6, v34
	v_mul_f32_e32 v6, v3, v36
	v_mul_f32_e32 v6, v110, v6
	v_mul_f32_e32 v35, v111, v35
	v_cvt_pk_bf16_f32 v35, v6, v35
	v_mul_f32_e32 v6, v3, v40
	v_mul_f32_e32 v36, v3, v38
	v_mul_f32_e32 v6, v116, v6
	v_mul_f32_e32 v36, v117, v36
	v_cvt_pk_bf16_f32 v36, v6, v36
	v_mul_f32_e32 v6, v3, v32
	v_mul_f32_e32 v32, v3, v33
	v_mul_f32_e32 v6, v118, v6
	v_mul_f32_e32 v32, v119, v32
	v_cvt_pk_bf16_f32 v37, v6, v32
	s_nop 0
	s_nop 0
	s_nop 0
	s_nop 0
	v_mul_f32_e32 v6, v3, v26
	s_waitcnt vmcnt(1)
	v_mul_f32_e32 v20, v133, v20
	s_waitcnt vmcnt(0)
	v_mul_f32_e32 v6, v124, v6
	v_mul_f32_e32 v24, v125, v24
	v_cvt_pk_bf16_f32 v38, v6, v24
	v_mul_f32_e32 v6, v3, v27
	v_mul_f32_e32 v6, v126, v6
	v_mul_f32_e32 v24, v3, v25
	v_mul_f32_e32 v24, v127, v24
	v_cvt_pk_bf16_f32 v39, v6, v24
	v_mul_f32_e32 v6, v3, v22
	v_mul_f32_e32 v6, v132, v6
	v_cvt_pk_bf16_f32 v40, v6, v20
	v_mul_f32_e32 v20, v3, v21
	v_mul_f32_e32 v6, v3, v23
	v_mul_f32_e32 v20, v135, v20
	v_mul_f32_e32 v6, v134, v6
	v_cvt_pk_bf16_f32 v41, v6, v20
	s_nop 0
	s_nop 0
	s_nop 0
	s_nop 0
	v_mul_f32_e32 v6, v3, v18
	v_mul_f32_e32 v18, v3, v19
	s_waitcnt vmcnt(0)
; __device__ __forceinline__ unsigned cvt_pk_bf16(float lo, float hi) { unsigned r; asm volatile("v_cvt_pk_bf16_f32 %0, %1, %2" : "=v"(r) : "v"(lo), "v"(hi)); return r; }
; __device__ __forceinline__ float bflo(unsigned w) { return __uint_as_float(w << 16); }
; __device__ __forceinline__ float bfhi(unsigned w) { return __uint_as_float(w & 0xffff0000u); }
; #define UNPK8(VV_, XX_) float XX_[8] = {bflo((VV_).x), bfhi((VV_).x), bflo((VV_).y), bfhi((VV_).y), bflo((VV_).z), bfhi((VV_).z), bflo((VV_).w), bfhi((VV_).w)}
; __device__ __forceinline__ void kvproj_task(int t, int l, const float* kvnorm, const float* kgain, const bf16_t* P, const bf16_t* WUKV, bf16_t* KB, bf16_t* VT, int fr, int fq) {
;     ...
;     for (int tb = 0; tb < 2; ++tb) { const int row = row0 + tb * 16; float ss = 0.f; u32x4 raw[4];
; #pragma unroll
;         for (int ks = 0; ks < 4; ++ks) { raw[ks] = ld8(P + (size_t)row * INP + ks * 32 + fq * 8); UNPK8(raw[ks], x);
;             ss += (x[0] * x[0] + x[1] * x[1]) + (x[2] * x[2] + x[3] * x[3]) + (x[4] * x[4] + x[5] * x[5]) + (x[6] * x[6] + x[7] * x[7]); }
; #pragma unroll
;         for (int cbr = 0; cbr < 2; ++cbr) { const u32x2 w = ld4(P + (size_t)row * INP + OFF_KROPE + cbr * 16 + fq * 4); kr[tb][cbr] = (f32x4){bflo(w.x), bfhi(w.x), bflo(w.y), bfhi(w.y)}; }
;         ss += __shfl_xor(ss, 16); ss += __shfl_xor(ss, 32);
;         const float rinv = rsqrtf(ss * (1.f / 128.f) + EPS);
; #pragma unroll
;         for (int ks = 0; ks < 4; ++ks) { const float* gp = kvnorm + l * 128 + ks * 32 + fq * 8; const f32x4 g0 = *(const f32x4*)gp, g1 = *(const f32x4*)(gp + 4); UNPK8(raw[ks], x); u32x4 o;
;             o.x = cvt_pk_bf16(x[0] * rinv * g0[0], x[1] * rinv * g0[1]); o.y = cvt_pk_bf16(x[2] * rinv * g0[2], x[3] * rinv * g0[3]);
;             o.z = cvt_pk_bf16(x[4] * rinv * g1[0], x[5] * rinv * g1[1]); o.w = cvt_pk_bf16(x[6] * rinv * g1[2], x[7] * rinv * g1[3]);
;             bfr[tb][ks] = asfrag(o); }
	v_mul_f32_e32 v6, v140, v6
	v_mul_f32_e32 v18, v141, v18
	v_cvt_pk_bf16_f32 v42, v6, v18
	v_mul_f32_e32 v6, v3, v8
	v_mul_f32_e32 v8, v3, v9
	v_mul_f32_e32 v6, v142, v6
	v_mul_f32_e32 v8, v143, v8
	v_cvt_pk_bf16_f32 v43, v6, v8
	v_mul_f32_e32 v6, v3, v30
	v_mul_f32_e32 v8, v3, v28
	v_mul_f32_e32 v6, v162, v6
	v_mul_f32_e32 v8, v163, v8
	v_cvt_pk_bf16_f32 v44, v6, v8
	v_mul_f32_e32 v6, v3, v16
	v_mul_f32_e32 v8, v3, v14
	v_mul_f32_e32 v6, v164, v6
	v_mul_f32_e32 v8, v165, v8
	v_cvt_pk_bf16_f32 v45, v6, v8
	s_nop 0
	s_nop 0
	s_nop 0
	s_nop 0
	v_mul_f32_e32 v6, v3, v31
	v_mul_f32_e32 v8, v3, v29
	s_waitcnt vmcnt(1)
	v_mul_f32_e32 v0, v0, v121
	s_waitcnt vmcnt(0)
	v_mul_f32_e32 v6, v6, v156
	v_mul_f32_e32 v8, v8, v157
	v_cvt_pk_bf16_f32 v46, v6, v8
	v_mul_f32_e32 v6, v3, v48
	v_mul_f32_e32 v6, v6, v158
	v_mul_f32_e32 v8, v3, v47
	v_mul_f32_e32 v8, v8, v159
	v_cvt_pk_bf16_f32 v47, v6, v8
	v_mul_f32_e32 v6, v3, v17
	v_mul_f32_e32 v6, v6, v112
	v_mul_f32_e32 v8, v3, v15
	v_mul_f32_e32 v8, v8, v113
	v_cvt_pk_bf16_f32 v48, v6, v8
	v_mul_f32_e32 v6, v3, v7
	v_mul_f32_e32 v6, v6, v120
	v_mad_i64_i32 v[14:15], s[6:7], v173, s84, v[94:95]
	v_cvt_pk_bf16_f32 v49, v6, v0
	flat_load_dwordx4 v[2:5], v[14:15]
	flat_load_dwordx4 v[6:9], v[14:15] offset:64
	s_waitcnt vmcnt(0) lgkmcnt(0)
	v_and_b32_e32 v33, 0xffff0000, v3
	v_and_b32_e32 v27, 0xffff0000, v7
	v_and_b32_e32 v26, 0xffff0000, v6
	v_lshlrev_b32_e32 v29, 16, v7
	v_lshlrev_b32_e32 v28, 16, v6
	v_pk_mul_f32 v[6:7], v[26:27], v[26:27]
	v_and_b32_e32 v23, 0xffff0000, v9
	v_and_b32_e32 v22, 0xffff0000, v8
	v_pk_fma_f32 v[6:7], v[28:29], v[28:29], v[6:7]
	v_lshlrev_b32_e32 v25, 16, v9
	v_lshlrev_b32_e32 v24, 16, v8
	v_pk_mul_f32 v[8:9], v[22:23], v[22:23]
	v_pk_add_f32 v[6:7], v[6:7], v[6:7] op_sel:[0,1] op_sel_hi:[1,0]
	v_pk_fma_f32 v[50:51], v[24:25], v[24:25], v[8:9]
	v_and_b32_e32 v57, 0xffff0000, v2
	v_pk_add_f32 v[52:53], v[50:51], v[6:7]
	flat_load_dwordx4 v[6:9], v[14:15] offset:128
	v_and_b32_e32 v56, 0xffff0000, v4
	flat_load_dwordx4 v[14:17], v[14:15] offset:192
	v_lshlrev_b32_e32 v32, 16, v3
	v_mul_f32_e32 v0, v33, v33
	v_lshlrev_b32_e32 v59, 16, v2
	v_lshlrev_b32_e32 v58, 16, v4
	v_pk_fma_f32 v[54:55], v[32:33], v[32:33], v[0:1] op_sel_hi:[1,1,0]
	v_lshlrev_b32_e32 v30, 16, v5
	v_and_b32_e32 v31, 0xffff0000, v5
	s_waitcnt vmcnt(0) lgkmcnt(0)
	v_lshlrev_b32_e32 v20, 16, v6
	v_and_b32_e32 v21, 0xffff0000, v6
	v_lshlrev_b32_e32 v18, 16, v7
	v_and_b32_e32 v19, 0xffff0000, v7
	v_mad_i64_i32 v[6:7], s[6:7], v173, s84, v[168:169]
	flat_load_dwordx2 v[68:69], v[6:7] offset:256
	flat_load_dwordx2 v[66:67], v[6:7] offset:288
	v_pk_mul_f32 v[6:7], v[56:57], v[56:57]
	v_and_b32_e32 v0, 0xffff0000, v17
	v_pk_fma_f32 v[6:7], v[58:59], v[58:59], v[6:7]
	v_lshlrev_b32_e32 v73, 16, v15
	v_pk_add_f32 v[54:55], v[6:7], v[54:55] op_sel:[1,0] op_sel_hi:[0,1]
	v_mul_f32_e32 v3, v0, v0
	v_pk_add_f32 v[6:7], v[6:7], v[54:55]
	v_pk_mov_b32 v[54:55], v[8:9], v[16:17] op_sel:[1,0]
	v_mul_f32_e32 v2, v21, v21
	v_and_b32_e32 v72, 0xffff0000, v15
	v_lshlrev_b32_e32 v15, 16, v17
	v_mul_f32_e32 v60, v73, v73
	v_lshlrev_b32_e32 v65, 16, v16
	v_and_b32_e32 v17, 0xffff0000, v55
	v_and_b32_e32 v16, 0xffff0000, v54
	v_pk_fma_f32 v[54:55], v[20:21], v[20:21], v[2:3] op_sel_hi:[1,1,0]
	v_mul_f32_e32 v2, v19, v19
	v_mul_f32_e32 v5, v72, v72
	v_and_b32_e32 v63, 0xffff0000, v14
	v_and_b32_e32 v62, 0xffff0000, v8
	v_mov_b32_e32 v55, v60
	v_pk_fma_f32 v[60:61], v[18:19], v[18:19], v[2:3] op_sel_hi:[1,1,0]
	v_lshlrev_b32_e32 v71, 16, v14
	v_lshlrev_b32_e32 v70, 16, v8
	v_lshlrev_b32_e32 v64, 16, v9
	v_pk_mul_f32 v[8:9], v[62:63], v[62:63]
	v_mov_b32_e32 v61, v5
	v_pk_fma_f32 v[8:9], v[70:71], v[70:71], v[8:9]
	v_pk_add_f32 v[4:5], v[54:55], v[60:61]
	v_mul_f32_e32 v2, v31, v31
	v_pk_add_f32 v[4:5], v[8:9], v[4:5]
	v_pk_mul_f32 v[8:9], v[16:17], v[16:17]
	v_mov_b32_e32 v54, v6
	v_pk_fma_f32 v[8:9], v[64:65], v[64:65], v[8:9]
	v_mov_b32_e32 v55, v15
	v_pk_add_f32 v[4:5], v[8:9], v[4:5]
	v_pk_fma_f32 v[8:9], v[30:31], v[30:31], v[2:3] op_sel_hi:[1,1,0]
	s_waitcnt vmcnt(0) lgkmcnt(0)
	v_and_b32_e32 v183, 0xffff0000, v69
	v_mov_b32_e32 v14, v8
	v_pk_add_f32 v[6:7], v[8:9], v[6:7]
	v_pk_mul_f32 v[8:9], v[14:15], v[54:55]
	v_and_b32_e32 v182, 0xffff0000, v68
	v_mov_b32_e32 v7, v9
	v_pk_add_f32 v[8:9], v[50:51], v[52:53] op_sel:[1,0] op_sel_hi:[0,1]
	v_mov_b32_e32 v9, v3
	v_pk_add_f32 v[2:3], v[6:7], v[8:9]
	v_lshlrev_b32_e32 v181, 16, v69
	v_pk_add_f32 v[2:3], v[2:3], v[4:5]
	v_lshlrev_b32_e32 v180, 16, v68
	v_add_f32_e32 v2, v2, v3
	ds_bpermute_b32 v3, v215, v2
	v_lshlrev_b32_e32 v170, 16, v67
	v_and_b32_e32 v172, 0xffff0000, v67
	v_lshlrev_b32_e32 v178, 16, v66
	v_and_b32_e32 v179, 0xffff0000, v66
	s_waitcnt lgkmcnt(0)
	v_add_f32_e32 v2, v2, v3
	ds_bpermute_b32 v3, v216, v2
	s_waitcnt lgkmcnt(0)
	v_add_f32_e32 v2, v2, v3
	v_fmamk_f32 v2, v2, 0x3c000000, v197
	v_cmp_gt_f32_e32 vcc, s47, v2
	v_mul_f32_e32 v3, 0x4b800000, v2
	s_nop 0
	v_cndmask_b32_e32 v2, v2, v3, vcc
	v_rsq_f32_e32 v2, v2
	s_nop 0
	v_mul_f32_e32 v3, 0x45800000, v2
	v_cndmask_b32_e32 v14, v2, v3, vcc
	s_nop 0
	s_nop 0
	s_nop 0
	s_nop 0
	v_mul_f32_e32 v50, v14, v59
	v_mul_f32_e32 v28, v14, v28
	v_mul_f32_e32 v26, v14, v26
	v_mul_f32_e32 v20, v14, v20
	v_mul_f32_e32 v0, v14, v0
	v_cmp_lt_i32_e32 vcc, s49, v171
	s_waitcnt vmcnt(0)
	v_mul_f32_e32 v6, v108, v50
	v_mul_f32_e32 v50, v14, v57
	v_mul_f32_e32 v7, v109, v50
	v_cvt_pk_bf16_f32 v50, v6, v7
	v_mul_f32_e32 v6, v14, v32
	v_mul_f32_e32 v6, v110, v6
	v_mul_f32_e32 v7, v14, v33
	v_mul_f32_e32 v7, v111, v7
	v_cvt_pk_bf16_f32 v51, v6, v7
	v_mul_f32_e32 v6, v14, v58
	v_mul_f32_e32 v2, v116, v6
	v_mul_f32_e32 v6, v14, v56
	v_mul_f32_e32 v3, v117, v6
	v_cvt_pk_bf16_f32 v52, v2, v3
	v_mul_f32_e32 v2, v14, v30
	v_mul_f32_e32 v3, v14, v31
	v_mul_f32_e32 v2, v118, v2
	v_mul_f32_e32 v3, v119, v3
	v_cvt_pk_bf16_f32 v53, v2, v3
	s_nop 0
	s_nop 0
	s_nop 0
	s_nop 0
	s_waitcnt vmcnt(0)
; __device__ __forceinline__ unsigned cvt_pk_bf16(float lo, float hi) { unsigned r; asm volatile("v_cvt_pk_bf16_f32 %0, %1, %2" : "=v"(r) : "v"(lo), "v"(hi)); return r; }
; #define MFMA16(a, b, c) __builtin_amdgcn_mfma_f32_16x16x32_bf16((a), (b), (c), 0, 0, 0)
; #define UNPK8(VV_, XX_) float XX_[8] = {bflo((VV_).x), bfhi((VV_).x), bflo((VV_).y), bfhi((VV_).y), bflo((VV_).z), bfhi((VV_).z), bflo((VV_).w), bfhi((VV_).w)}
; __device__ __forceinline__ void kvproj_task(int t, int l, const float* kvnorm, const float* kgain, const bf16_t* P, const bf16_t* WUKV, bf16_t* KB, bf16_t* VT, int fr, int fq) {
;     ...
;         for (int ks = 0; ks < 4; ++ks) { const float* gp = kvnorm + l * 128 + ks * 32 + fq * 8; const f32x4 g0 = *(const f32x4*)gp, g1 = *(const f32x4*)(gp + 4); UNPK8(raw[ks], x); u32x4 o;
;             o.x = cvt_pk_bf16(x[0] * rinv * g0[0], x[1] * rinv * g0[1]); o.y = cvt_pk_bf16(x[2] * rinv * g0[2], x[3] * rinv * g0[3]);
;             o.z = cvt_pk_bf16(x[4] * rinv * g1[0], x[5] * rinv * g1[1]); o.w = cvt_pk_bf16(x[6] * rinv * g1[2], x[7] * rinv * g1[3]);
;             bfr[tb][ks] = asfrag(o); }
;         skr[tb] = (kr[tb][0][0] * kr[tb][0][0] + kr[tb][0][1] * kr[tb][0][1]) + (kr[tb][0][2] * kr[tb][0][2] + kr[tb][0][3] * kr[tb][0][3]) + (kr[tb][1][0] * kr[tb][1][0] + kr[tb][1][1] * kr[tb][1][1]) + (kr[tb][1][2] * kr[tb][1][2] + kr[tb][1][3] * kr[tb][1][3]); }
;     const bf16_t* wk0 = WUKV + ((size_t)l * 512 + h * 128 + fr) * 128 + fq * 8;
;     bf16x8 wf[2][4];
; #pragma unroll
;     for (int ks = 0; ks < 4; ++ks) wf[0][ks] = asfrag(ld8(wk0 + ks * 32));
;     f32x4 acc[2][8];
; #pragma unroll
;     for (int cb = 0; cb < 8; ++cb) { acc[0][cb] = (f32x4){0.f, 0.f, 0.f, 0.f}; acc[1][cb] = acc[0][cb];
;         const int nrow = cb < 7 ? (cb + 1) * 16 : 0;
; #pragma unroll
;         for (int ks = 0; ks < 4; ++ks) wf[(cb + 1) & 1][ks] = asfrag(ld8(wk0 + (size_t)nrow * 128 + ks * 32));
; #pragma unroll
;         for (int ks = 0; ks < 4; ++ks) { acc[0][cb] = MFMA16(wf[cb & 1][ks], bfr[0][ks], acc[0][cb]); acc[1][cb] = MFMA16(wf[cb & 1][ks], bfr[1][ks], acc[1][cb]); } }
	v_mul_f32_e32 v6, v124, v28
	v_mul_f32_e32 v7, v125, v26
	v_cvt_pk_bf16_f32 v54, v6, v7
	v_mul_f32_e32 v6, v14, v29
	v_mul_f32_e32 v6, v126, v6
	v_mul_f32_e32 v7, v14, v27
	v_mul_f32_e32 v7, v127, v7
	v_cvt_pk_bf16_f32 v55, v6, v7
	v_mul_f32_e32 v6, v14, v24
	v_mul_f32_e32 v2, v132, v6
	v_mul_f32_e32 v6, v14, v22
	v_mul_f32_e32 v3, v133, v6
	v_cvt_pk_bf16_f32 v56, v2, v3
	v_mul_f32_e32 v2, v14, v25
	v_mul_f32_e32 v3, v14, v23
	v_mul_f32_e32 v2, v134, v2
	v_mul_f32_e32 v3, v135, v3
	v_cvt_pk_bf16_f32 v57, v2, v3
	s_nop 0
	s_nop 0
	s_nop 0
	s_nop 0
	s_waitcnt vmcnt(0)
	v_mul_f32_e32 v6, v140, v20
	v_mul_f32_e32 v20, v14, v21
	v_mul_f32_e32 v7, v141, v20
	v_cvt_pk_bf16_f32 v58, v6, v7
	v_mul_f32_e32 v6, v14, v18
	v_mul_f32_e32 v6, v142, v6
	v_mul_f32_e32 v7, v14, v19
	v_mul_f32_e32 v7, v143, v7
	v_cvt_pk_bf16_f32 v59, v6, v7
	v_mul_f32_e32 v6, v14, v70
	v_mul_f32_e32 v2, v162, v6
	v_mul_f32_e32 v6, v14, v62
	v_mul_f32_e32 v3, v163, v6
	v_cvt_pk_bf16_f32 v60, v2, v3
	v_mul_f32_e32 v2, v14, v64
	v_mul_f32_e32 v3, v14, v16
	v_mul_f32_e32 v2, v164, v2
	v_mul_f32_e32 v3, v165, v3
	v_cvt_pk_bf16_f32 v61, v2, v3
	s_nop 0
	s_nop 0
	s_nop 0
	s_nop 0
	v_mul_f32_e32 v16, v14, v71
	s_waitcnt vmcnt(1)
	v_mul_f32_e32 v0, v0, v121
	s_waitcnt vmcnt(0)
	v_mul_f32_e32 v6, v16, v156
	v_mul_f32_e32 v16, v14, v63
	v_mul_f32_e32 v7, v16, v157
	v_cvt_pk_bf16_f32 v62, v6, v7
	v_mul_f32_e32 v6, v14, v73
	v_mul_f32_e32 v6, v6, v158
	v_mul_f32_e32 v7, v14, v72
	v_mul_f32_e32 v7, v7, v159
	v_cvt_pk_bf16_f32 v63, v6, v7
	v_mul_f32_e32 v6, v14, v65
	v_mul_f32_e32 v2, v6, v112
	v_mul_f32_e32 v6, v14, v17
	v_mul_f32_e32 v3, v6, v113
	v_cvt_pk_bf16_f32 v64, v2, v3
	v_mul_f32_e32 v2, v14, v15
	v_mul_f32_e32 v2, v2, v120
	v_cvt_pk_bf16_f32 v65, v2, v0
	v_pk_mul_f32 v[2:3], v[182:183], v[182:183]
	v_add_u32_e32 v0, 0xffffc000, v171
	v_pk_fma_f32 v[192:193], v[180:181], v[180:181], v[2:3]
	flat_load_dwordx4 v[2:5], v[104:105]
	flat_load_dwordx4 v[6:9], v[104:105] offset:64
	flat_load_dwordx4 v[14:17], v[104:105] offset:128
	flat_load_dwordx4 v[18:21], v[104:105] offset:192
	flat_load_dwordx4 v[22:25], v[106:107]
	flat_load_dwordx4 v[26:29], v[106:107] offset:64
	flat_load_dwordx4 v[30:33], v[106:107] offset:128
	flat_load_dwordx4 v[74:77], v[106:107] offset:192
	s_waitcnt vmcnt(0) lgkmcnt(0)
	v_mfma_f32_16x16x32_bf16 v[66:69], v[2:5], v[34:37], 0
	v_mfma_f32_16x16x32_bf16 v[2:5], v[2:5], v[50:53], 0
	v_mfma_f32_16x16x32_bf16 v[66:69], v[6:9], v[38:41], v[66:69]
	v_mfma_f32_16x16x32_bf16 v[2:5], v[6:9], v[54:57], v[2:5]
	v_mfma_f32_16x16x32_bf16 v[6:9], v[14:17], v[42:45], v[66:69]
	v_mfma_f32_16x16x32_bf16 v[2:5], v[14:17], v[58:61], v[2:5]
	v_mfma_f32_16x16x32_bf16 v[66:69], v[18:21], v[46:49], v[6:9]
	v_mfma_f32_16x16x32_bf16 v[6:9], v[22:25], v[34:37], 0
	v_mfma_f32_16x16x32_bf16 v[22:25], v[22:25], v[50:53], 0
	s_nop 5
	v_mov_b32_e32 v177, v67
	v_mov_b32_e32 v175, v66
	v_mfma_f32_16x16x32_bf16 v[2:5], v[18:21], v[62:65], v[2:5]
	flat_load_dwordx4 v[14:17], v[114:115]
	flat_load_dwordx4 v[18:21], v[114:115] offset:64
	flat_load_dwordx4 v[78:81], v[114:115] offset:128
	flat_load_dwordx4 v[82:85], v[114:115] offset:192
	v_mfma_f32_16x16x32_bf16 v[6:9], v[26:29], v[38:41], v[6:9]
	v_mfma_f32_16x16x32_bf16 v[22:25], v[26:29], v[54:57], v[22:25]
	v_mfma_f32_16x16x32_bf16 v[6:9], v[30:33], v[42:45], v[6:9]
	v_mfma_f32_16x16x32_bf16 v[22:25], v[30:33], v[58:61], v[22:25]
	v_mfma_f32_16x16x32_bf16 v[70:73], v[74:77], v[46:49], v[6:9]
	v_mfma_f32_16x16x32_bf16 v[6:9], v[74:77], v[62:65], v[22:25]
	s_nop 5
	flat_load_dwordx4 v[22:25], v[122:123]
	flat_load_dwordx4 v[26:29], v[122:123] offset:64
	flat_load_dwordx4 v[30:33], v[122:123] offset:128
	flat_load_dwordx4 v[74:77], v[122:123] offset:192
	s_waitcnt vmcnt(0) lgkmcnt(0)
	v_mfma_f32_16x16x32_bf16 v[86:89], v[14:17], v[34:37], 0
	v_mfma_f32_16x16x32_bf16 v[14:17], v[14:17], v[50:53], 0
	v_mfma_f32_16x16x32_bf16 v[86:89], v[18:21], v[38:41], v[86:89]
	v_mfma_f32_16x16x32_bf16 v[14:17], v[18:21], v[54:57], v[14:17]
	v_mfma_f32_16x16x32_bf16 v[18:21], v[78:81], v[42:45], v[86:89]
	v_mfma_f32_16x16x32_bf16 v[86:89], v[22:25], v[34:37], 0
	v_mfma_f32_16x16x32_bf16 v[22:25], v[22:25], v[50:53], 0
	v_mfma_f32_16x16x32_bf16 v[14:17], v[78:81], v[58:61], v[14:17]
	v_mfma_f32_16x16x32_bf16 v[86:89], v[26:29], v[38:41], v[86:89]
	v_mfma_f32_16x16x32_bf16 v[22:25], v[26:29], v[54:57], v[22:25]
	v_mfma_f32_16x16x32_bf16 v[78:81], v[82:85], v[46:49], v[18:21]
	v_mfma_f32_16x16x32_bf16 v[18:21], v[82:85], v[62:65], v[14:17]
	s_nop 3
	flat_load_dwordx4 v[14:17], v[130:131]
	flat_load_dwordx4 v[82:85], v[130:131] offset:64
	flat_load_dwordx4 v[90:93], v[130:131] offset:128
	flat_load_dwordx4 v[222:225], v[130:131] offset:192
	v_mfma_f32_16x16x32_bf16 v[26:29], v[30:33], v[42:45], v[86:89]
	v_mfma_f32_16x16x32_bf16 v[22:25], v[30:33], v[58:61], v[22:25]
	v_mfma_f32_16x16x32_bf16 v[86:89], v[74:77], v[46:49], v[26:29]
	v_mfma_f32_16x16x32_bf16 v[26:29], v[74:77], v[62:65], v[22:25]
	s_nop 5
	flat_load_dwordx4 v[22:25], v[138:139]
	flat_load_dwordx4 v[30:33], v[138:139] offset:64
	flat_load_dwordx4 v[226:229], v[138:139] offset:128
	flat_load_dwordx4 v[230:233], v[138:139] offset:192
	s_waitcnt vmcnt(0) lgkmcnt(0)
; __device__ __forceinline__ unsigned cvt_pk_bf16(float lo, float hi) { unsigned r; asm volatile("v_cvt_pk_bf16_f32 %0, %1, %2" : "=v"(r) : "v"(lo), "v"(hi)); return r; }
; #define MFMA16(a, b, c) __builtin_amdgcn_mfma_f32_16x16x32_bf16((a), (b), (c), 0, 0, 0)
; __device__ __forceinline__ void kvproj_task(int t, int l, const float* kvnorm, const float* kgain, const bf16_t* P, const bf16_t* WUKV, bf16_t* KB, bf16_t* VT, int fr, int fq) {
;     ...
; #pragma unroll
;     for (int cb = 0; cb < 8; ++cb) { acc[0][cb] = (f32x4){0.f, 0.f, 0.f, 0.f}; acc[1][cb] = acc[0][cb];
;         const int nrow = cb < 7 ? (cb + 1) * 16 : 0;
; #pragma unroll
;         for (int ks = 0; ks < 4; ++ks) wf[(cb + 1) & 1][ks] = asfrag(ld8(wk0 + (size_t)nrow * 128 + ks * 32));
; #pragma unroll
;         for (int ks = 0; ks < 4; ++ks) { acc[0][cb] = MFMA16(wf[cb & 1][ks], bfr[0][ks], acc[0][cb]); acc[1][cb] = MFMA16(wf[cb & 1][ks], bfr[1][ks], acc[1][cb]); } }
; #pragma unroll
;     for (int tb = 0; tb < 2; ++tb) { const int row = row0 + tb * 16, rr = isc ? row - ML : row;
;         const int b = isc ? rr >> 8 : rr >> 11, tpos = isc ? rr & 255 : rr & 2047, key = isc ? tpos : 256 + tpos;
;         float s2 = skr[tb];
; #pragma unroll
;         for (int cb = 0; cb < 4; ++cb) s2 += (acc[tb][cb][0] * acc[tb][cb][0] + acc[tb][cb][1] * acc[tb][cb][1]) + (acc[tb][cb][2] * acc[tb][cb][2] + acc[tb][cb][3] * acc[tb][cb][3]);
;         s2 += __shfl_xor(s2, 16); s2 += __shfl_xor(s2, 32);
;         const float rh = rsqrtf(s2 * (1.f / 96.f) + EPS);
;         bf16_t* kdst = KB + ((size_t)(b * 4 + h) * NKEY + key) * 96;
; #pragma unroll
;         for (int cb = 0; cb < 6; ++cb) { const f32x4 kg = *(const f32x4*)(kgain + l * 96 + cb * 16 + fq * 4); f32x4 v = (cb < 4 ? acc[tb][cb < 4 ? cb : 0] : kr[tb][cb >= 4 ? cb - 4 : 0]) * rh * kg;
;             if (cb >= 4) { const f32x4 rv = rope16(v, fq, (float)(cb == 4 ? (tpos >> 6) : (tpos & 63))); if (!isc) v = rv; }
;             u32x2 w; w.x = cvt_pk_bf16(v[0], v[1]); w.y = cvt_pk_bf16(v[2], v[3]);
;             *(u32x2*)(kdst + cb * 16 + fq * 4) = w; }
	v_mfma_f32_16x16x32_bf16 v[74:77], v[14:17], v[34:37], 0
	v_mfma_f32_16x16x32_bf16 v[14:17], v[14:17], v[50:53], 0
	v_mfma_f32_16x16x32_bf16 v[74:77], v[82:85], v[38:41], v[74:77]
	v_mfma_f32_16x16x32_bf16 v[14:17], v[82:85], v[54:57], v[14:17]
	v_mfma_f32_16x16x32_bf16 v[82:85], v[22:25], v[34:37], 0
	v_mfma_f32_16x16x32_bf16 v[22:25], v[22:25], v[50:53], 0
	v_mfma_f32_16x16x32_bf16 v[82:85], v[30:33], v[38:41], v[82:85]
	v_mfma_f32_16x16x32_bf16 v[22:25], v[30:33], v[54:57], v[22:25]
	v_mfma_f32_16x16x32_bf16 v[74:77], v[90:93], v[42:45], v[74:77]
	v_mfma_f32_16x16x32_bf16 v[14:17], v[90:93], v[58:61], v[14:17]
	v_mfma_f32_16x16x32_bf16 v[30:33], v[226:229], v[42:45], v[82:85]
	v_mfma_f32_16x16x32_bf16 v[22:25], v[226:229], v[58:61], v[22:25]
	v_mfma_f32_16x16x32_bf16 v[74:77], v[222:225], v[46:49], v[74:77]
	v_mfma_f32_16x16x32_bf16 v[14:17], v[222:225], v[62:65], v[14:17]
	flat_load_dwordx4 v[90:93], v[146:147]
	flat_load_dwordx4 v[222:225], v[146:147] offset:64
	flat_load_dwordx4 v[234:237], v[146:147] offset:128
	flat_load_dwordx4 v[238:241], v[146:147] offset:192
	v_mfma_f32_16x16x32_bf16 v[82:85], v[230:233], v[46:49], v[30:33]
	v_mfma_f32_16x16x32_bf16 v[22:25], v[230:233], v[62:65], v[22:25]
	flat_load_dwordx4 v[226:229], v[160:161]
	flat_load_dwordx4 v[230:233], v[160:161] offset:64
	flat_load_dwordx4 v[242:245], v[160:161] offset:128
	flat_load_dwordx4 v[246:249], v[160:161] offset:192
	s_waitcnt vmcnt(0) lgkmcnt(0)
	v_mfma_f32_16x16x32_bf16 v[30:33], v[90:93], v[34:37], 0
	v_mfma_f32_16x16x32_bf16 v[34:37], v[226:229], v[34:37], 0
	v_mfma_f32_16x16x32_bf16 v[90:93], v[90:93], v[50:53], 0
	v_mfma_f32_16x16x32_bf16 v[50:53], v[226:229], v[50:53], 0
	v_mfma_f32_16x16x32_bf16 v[30:33], v[222:225], v[38:41], v[30:33]
	v_mfma_f32_16x16x32_bf16 v[34:37], v[230:233], v[38:41], v[34:37]
	v_mfma_f32_16x16x32_bf16 v[38:41], v[230:233], v[54:57], v[50:53]
	v_mfma_f32_16x16x32_bf16 v[90:93], v[222:225], v[54:57], v[90:93]
	v_cndmask_b32_e32 v54, v171, v0, vcc
	v_mul_f32_e32 v0, v68, v68
	s_nop 1
	v_mul_f32_e32 v50, v69, v69
	v_mfma_f32_16x16x32_bf16 v[30:33], v[234:237], v[42:45], v[30:33]
	v_mfma_f32_16x16x32_bf16 v[34:37], v[242:245], v[42:45], v[34:37]
	v_mfma_f32_16x16x32_bf16 v[42:45], v[242:245], v[58:61], v[38:41]
	v_mfma_f32_16x16x32_bf16 v[222:225], v[234:237], v[58:61], v[90:93]
	v_mfma_f32_16x16x32_bf16 v[90:93], v[238:241], v[46:49], v[30:33]
	v_mfma_f32_16x16x32_bf16 v[38:41], v[246:249], v[46:49], v[34:37]
	v_add_f32_e64 v46, v190, v191
	v_add_f32_e64 v47, v191, v190
	v_mov_b32_e32 v47, v0
	v_mul_f32_e32 v0, v185, v185
	v_pk_fma_f32 v[48:49], v[184:185], v[184:185], v[0:1] op_sel_hi:[1,1,0]
	v_mfma_f32_16x16x32_bf16 v[34:37], v[246:249], v[62:65], v[42:45]
	v_mov_b32_e32 v49, v50
	v_pk_add_f32 v[46:47], v[46:47], v[48:49]
	v_pk_mul_f32 v[48:49], v[70:71], v[70:71]
	v_pk_mul_f32 v[44:45], v[176:177], v[176:177]
	v_mul_f32_e32 v0, v86, v86
	v_pk_fma_f32 v[44:45], v[174:175], v[174:175], v[44:45]
	v_cndmask_b32_e32 v43, v200, v201, vcc
	v_pk_add_f32 v[44:45], v[44:45], v[46:47]
	v_pk_mul_f32 v[46:47], v[72:73], v[72:73]
	v_pk_add_f32 v[44:45], v[44:45], v[44:45] op_sel:[0,1] op_sel_hi:[1,0]
	v_pk_mov_b32 v[50:51], v[48:49], v[46:47] op_sel:[1,0]
	v_mov_b32_e32 v49, v47
	v_pk_add_f32 v[46:47], v[50:51], v[48:49]
	v_mul_f32_e32 v48, v87, v87
	v_pk_add_f32 v[46:47], v[46:47], v[46:47] op_sel:[0,1] op_sel_hi:[1,0]
	v_mov_b32_e32 v45, v0
	v_mov_b32_e32 v47, v48
	v_mul_f32_e32 v0, v79, v79
	v_mul_f32_e32 v49, v88, v88
	v_pk_add_f32 v[44:45], v[44:45], v[46:47]
	v_pk_fma_f32 v[46:47], v[78:79], v[78:79], v[0:1] op_sel_hi:[1,1,0]
	v_mul_f32_e32 v0, v81, v81
	v_mul_f32_e32 v50, v89, v89
	v_mov_b32_e32 v47, v49
	v_pk_fma_f32 v[48:49], v[80:81], v[80:81], v[0:1] op_sel_hi:[1,1,0]
	v_cndmask_b32_e64 v42, 11, 8, vcc
	v_mov_b32_e32 v49, v50
	v_pk_add_f32 v[46:47], v[46:47], v[48:49]
	v_and_b32_e32 v55, v54, v43
	v_pk_add_f32 v[44:45], v[44:45], v[46:47]
	v_add_u32_e32 v52, 0x100, v55
	v_add_f32_e32 v44, v44, v45
	ds_bpermute_b32 v46, v215, v44
	v_ashrrev_i32_e32 v45, v42, v54
	v_cndmask_b32_e32 v0, v52, v55, vcc
	v_lshl_or_b32 v50, v45, 2, s22
	v_lshrrev_b32_e32 v49, 6, v55
	s_waitcnt lgkmcnt(0)
	v_add_f32_e32 v44, v44, v46
	ds_bpermute_b32 v46, v216, v44
	v_mfma_f32_16x16x32_bf16 v[30:33], v[238:241], v[62:65], v[222:225]
	v_and_b32_e32 v64, 47, v54
	v_mov_b32_e32 v175, v176
	v_ashrrev_i32_e32 v51, 31, v50
	s_waitcnt lgkmcnt(0)
	v_add_f32_e32 v44, v44, v46
	v_fmamk_f32 v44, v44, 0x3c2aaaab, v197
	v_cmp_gt_f32_e64 s[38:39], s47, v44
	v_mul_f32_e32 v46, 0x4b800000, v44
	s_nop 0
	v_cndmask_b32_e64 v44, v44, v46, s[38:39]
	v_rsq_f32_e32 v44, v44
	s_nop 0
	v_mul_f32_e32 v46, 0x45800000, v44
	v_cndmask_b32_e64 v48, v44, v46, s[38:39]
	v_mad_i64_i32 v[44:45], s[6:7], v50, s9, v[0:1]
	v_mad_u64_u32 v[52:53], s[6:7], v44, s14, v[102:103]
	v_mad_i32_i24 v53, v45, s14, v53
	global_load_dwordx4 v[44:47], v[100:101], off
	v_pk_mul_f32 v[56:57], v[66:67], v[48:49] op_sel_hi:[1,0]
	v_pk_mul_f32 v[54:55], v[68:69], v[48:49] op_sel_hi:[1,0]
	v_lshlrev_b32_e32 v0, 1, v0
	s_waitcnt vmcnt(0)
	v_pk_mul_f32 v[44:45], v[44:45], v[56:57]
	v_pk_mul_f32 v[46:47], v[46:47], v[54:55]
	v_cvt_pk_bf16_f32 v44, v44, v45
	v_pk_mul_f32 v[56:57], v[70:71], v[48:49] op_sel_hi:[1,0]
	v_cvt_pk_bf16_f32 v45, v46, v47
	flat_store_dwordx2 v[52:53], v[44:45]
	global_load_dwordx4 v[44:47], v[100:101], off offset:64
	v_pk_mul_f32 v[54:55], v[72:73], v[48:49] op_sel_hi:[1,0]
	s_waitcnt vmcnt(0)
; __device__ __forceinline__ unsigned cvt_pk_bf16(float lo, float hi) { unsigned r; asm volatile("v_cvt_pk_bf16_f32 %0, %1, %2" : "=v"(r) : "v"(lo), "v"(hi)); return r; }
; __device__ __forceinline__ bf16_t tobf(float f) { return (bf16_t)(cvt_pk_bf16(f, 0.f) & 0xffffu); }
; __device__ __forceinline__ f32x4 rope16(f32x4 v, int fq, float pos) {
;     f32x4 pr; pr[0] = __shfl_xor(v[0], 32); pr[1] = __shfl_xor(v[1], 32); pr[2] = __shfl_xor(v[2], 32); pr[3] = __shfl_xor(v[3], 32);
;     f32x4 o;
; #pragma unroll
;     for (int q = 0; q < 4; ++q) { const int f = (fq * 4 + q) & 7; const float inv = __builtin_amdgcn_exp2f(-(float)f * 1.6609640474f); float sn, cs; __sincosf(pos * inv, &sn, &cs);
;         o[q] = fq < 2 ? v[q] * cs - pr[q] * sn : pr[q] * sn + v[q] * cs; }
;     return o;
; }
; __device__ __forceinline__ void kvproj_task(int t, int l, const float* kvnorm, const float* kgain, const bf16_t* P, const bf16_t* WUKV, bf16_t* KB, bf16_t* VT, int fr, int fq) {
;     ...
;     for (int tb = 0; tb < 2; ++tb) { const int row = row0 + tb * 16, rr = isc ? row - ML : row;
;         const int b = isc ? rr >> 8 : rr >> 11, tpos = isc ? rr & 255 : rr & 2047, key = isc ? tpos : 256 + tpos;
;         float s2 = skr[tb];
; #pragma unroll
;         for (int cb = 0; cb < 4; ++cb) s2 += (acc[tb][cb][0] * acc[tb][cb][0] + acc[tb][cb][1] * acc[tb][cb][1]) + (acc[tb][cb][2] * acc[tb][cb][2] + acc[tb][cb][3] * acc[tb][cb][3]);
;         s2 += __shfl_xor(s2, 16); s2 += __shfl_xor(s2, 32);
;         const float rh = rsqrtf(s2 * (1.f / 96.f) + EPS);
;         bf16_t* kdst = KB + ((size_t)(b * 4 + h) * NKEY + key) * 96;
; #pragma unroll
;         for (int cb = 0; cb < 6; ++cb) { const f32x4 kg = *(const f32x4*)(kgain + l * 96 + cb * 16 + fq * 4); f32x4 v = (cb < 4 ? acc[tb][cb < 4 ? cb : 0] : kr[tb][cb >= 4 ? cb - 4 : 0]) * rh * kg;
;             if (cb >= 4) { const f32x4 rv = rope16(v, fq, (float)(cb == 4 ? (tpos >> 6) : (tpos & 63))); if (!isc) v = rv; }
;             u32x2 w; w.x = cvt_pk_bf16(v[0], v[1]); w.y = cvt_pk_bf16(v[2], v[3]);
;             *(u32x2*)(kdst + cb * 16 + fq * 4) = w; }
; #pragma unroll
;         for (int cb = 4; cb < 8; ++cb)
; #pragma unroll
;             for (int q = 0; q < 4; ++q) VT[((size_t)(b * 4 + h) * 64 + (cb - 4) * 16 + fq * 4 + q) * NKEY + key] = tobf(acc[tb][cb][q]); }
	v_pk_mul_f32 v[44:45], v[44:45], v[56:57]
	v_pk_mul_f32 v[46:47], v[46:47], v[54:55]
	v_cvt_pk_bf16_f32 v44, v44, v45
	v_pk_mul_f32 v[56:57], v[78:79], v[48:49] op_sel_hi:[1,0]
	v_cvt_pk_bf16_f32 v45, v46, v47
	flat_store_dwordx2 v[52:53], v[44:45] offset:32
	global_load_dwordx4 v[44:47], v[100:101], off offset:128
	v_pk_mul_f32 v[54:55], v[80:81], v[48:49] op_sel_hi:[1,0]
	s_waitcnt vmcnt(0)
	v_pk_mul_f32 v[44:45], v[44:45], v[56:57]
	v_pk_mul_f32 v[46:47], v[46:47], v[54:55]
	v_cvt_pk_bf16_f32 v44, v44, v45
	v_pk_mul_f32 v[56:57], v[86:87], v[48:49] op_sel_hi:[1,0]
	v_cvt_pk_bf16_f32 v45, v46, v47
	flat_store_dwordx2 v[52:53], v[44:45] offset:64
	global_load_dwordx4 v[44:47], v[100:101], off offset:192
	v_pk_mul_f32 v[54:55], v[88:89], v[48:49] op_sel_hi:[1,0]
	s_waitcnt vmcnt(0)
	v_pk_mul_f32 v[44:45], v[56:57], v[44:45]
	v_pk_mul_f32 v[46:47], v[54:55], v[46:47]
	v_cvt_pk_bf16_f32 v44, v44, v45
	v_mov_b32_e32 v54, v186
	v_cvt_pk_bf16_f32 v45, v46, v47
	flat_store_dwordx2 v[52:53], v[44:45] offset:96
	global_load_dwordx4 v[44:47], v[100:101], off offset:256
	v_mov_b32_e32 v55, v188
	v_mov_b32_e32 v188, v187
	v_pk_mul_f32 v[54:55], v[48:49], v[54:55] op_sel_hi:[0,1]
	v_pk_mul_f32 v[56:57], v[48:49], v[188:189] op_sel_hi:[0,1]
	v_cvt_f32_ubyte0_e32 v49, v49
	v_mul_f32_e32 v58, v217, v49
	v_mul_f32_e32 v59, 0.15915494, v58
	v_cos_f32_e32 v58, v59
	v_sin_f32_e32 v60, v59
	v_mul_f32_e32 v59, v218, v49
	v_mul_f32_e32 v61, 0.15915494, v59
	v_cos_f32_e32 v59, v61
	v_sin_f32_e32 v61, v61
	s_waitcnt vmcnt(0)
	v_pk_mul_f32 v[44:45], v[54:55], v[44:45]
	ds_bpermute_b32 v54, v216, v44
	ds_bpermute_b32 v55, v216, v45
	v_pk_mul_f32 v[46:47], v[56:57], v[46:47]
	ds_bpermute_b32 v56, v216, v46
	ds_bpermute_b32 v57, v216, v47
	s_waitcnt lgkmcnt(0)
	v_pk_mul_f32 v[54:55], v[60:61], v[54:55]
	v_mul_f32_e32 v60, v219, v49
	v_mul_f32_e32 v49, v220, v49
	v_mul_f32_e32 v61, 0.15915494, v60
	v_mul_f32_e32 v49, 0.15915494, v49
	v_sin_f32_e32 v62, v61
	v_sin_f32_e32 v63, v49
	v_cos_f32_e32 v60, v61
	v_cos_f32_e32 v61, v49
	v_cndmask_b32_e64 v55, v55, -v55, s[36:37]
	v_pk_mul_f32 v[56:57], v[62:63], v[56:57]
	v_cndmask_b32_e64 v54, v54, -v54, s[36:37]
	v_cndmask_b32_e64 v57, v57, -v57, s[36:37]
	v_cndmask_b32_e64 v56, v56, -v56, s[36:37]
	v_pk_fma_f32 v[54:55], v[58:59], v[44:45], v[54:55]
	v_pk_fma_f32 v[56:57], v[60:61], v[46:47], v[56:57]
	v_cndmask_b32_e32 v44, v54, v44, vcc
	v_cndmask_b32_e32 v45, v55, v45, vcc
	v_cndmask_b32_e32 v46, v56, v46, vcc
	v_cndmask_b32_e32 v47, v57, v47, vcc
	v_cvt_pk_bf16_f32 v44, v44, v45
	v_cvt_pk_bf16_f32 v45, v46, v47
	flat_store_dwordx2 v[52:53], v[44:45] offset:128
	global_load_dwordx4 v[44:47], v[100:101], off offset:320
	v_cvt_f32_ubyte0_e32 v61, v64
	v_mul_f32_e32 v56, v217, v61
	v_pk_mul_f32 v[54:55], v[48:49], v[184:185] op_sel_hi:[0,1]
	v_mul_f32_e32 v57, 0.15915494, v56
	v_pk_mul_f32 v[48:49], v[48:49], v[174:175] op_sel_hi:[0,1]
	v_cos_f32_e32 v56, v57
	v_sin_f32_e32 v58, v57
	v_mul_f32_e32 v57, v218, v61
	v_mul_f32_e32 v59, 0.15915494, v57
	v_cos_f32_e32 v57, v59
	v_sin_f32_e32 v59, v59
	s_waitcnt vmcnt(0)
	v_pk_mul_f32 v[44:45], v[54:55], v[44:45]
	v_pk_mul_f32 v[46:47], v[48:49], v[46:47]
	ds_bpermute_b32 v48, v216, v44
	ds_bpermute_b32 v49, v216, v45
	ds_bpermute_b32 v54, v216, v46
	ds_bpermute_b32 v55, v216, v47
	s_waitcnt lgkmcnt(0)
	v_pk_mul_f32 v[48:49], v[58:59], v[48:49]
	v_mul_f32_e32 v58, v219, v61
	v_mul_f32_e32 v59, 0.15915494, v58
	v_cos_f32_e32 v58, v59
	v_sin_f32_e32 v60, v59
	v_mul_f32_e32 v59, v220, v61
	v_mul_f32_e32 v61, 0.15915494, v59
	v_cos_f32_e32 v59, v61
	v_sin_f32_e32 v61, v61
	v_cndmask_b32_e64 v49, v49, -v49, s[36:37]
	v_cndmask_b32_e64 v48, v48, -v48, s[36:37]
	v_pk_fma_f32 v[48:49], v[56:57], v[44:45], v[48:49]
	v_pk_mul_f32 v[54:55], v[60:61], v[54:55]
	v_cndmask_b32_e32 v44, v48, v44, vcc
	v_cndmask_b32_e64 v55, v55, -v55, s[36:37]
	v_cndmask_b32_e64 v54, v54, -v54, s[36:37]
	v_pk_fma_f32 v[54:55], v[58:59], v[46:47], v[54:55]
	v_cndmask_b32_e32 v45, v49, v45, vcc
	v_cndmask_b32_e32 v46, v54, v46, vcc
	v_cndmask_b32_e32 v47, v55, v47, vcc
	v_cvt_pk_bf16_f32 v44, v44, v45
	v_cvt_pk_bf16_f32 v45, v46, v47
	v_lshlrev_b64 v[46:47], 6, v[50:51]
	flat_store_dwordx2 v[52:53], v[44:45] offset:160
	v_lshl_add_u64 v[44:45], s[40:41], 0, v[0:1]
	v_or_b32_e32 v0, v46, v96
	v_mad_u64_u32 v[44:45], s[6:7], v0, s88, v[44:45]
	v_cvt_pk_bf16_f32 v46, v74, v1
	v_mad_i32_i24 v45, v47, s88, v45
	flat_store_short v[44:45], v46
	v_add_co_u32_e64 v46, s[38:39], s19, v44
	v_cvt_pk_bf16_f32 v0, v75, v1
	s_nop 1
	v_addc_co_u32_e64 v47, s[38:39], 0, v45, s[38:39]
	flat_store_short v[46:47], v0 offset:512
	v_add_co_u32_e64 v46, s[38:39], s33, v44
	v_cvt_pk_bf16_f32 v0, v76, v1
	s_nop 1
	v_addc_co_u32_e64 v47, s[38:39], 0, v45, s[38:39]
	flat_store_short v[46:47], v0 offset:1024
	v_add_co_u32_e64 v46, s[38:39], s23, v44
	v_cvt_pk_bf16_f32 v0, v77, v1
	s_nop 1
	v_addc_co_u32_e64 v47, s[38:39], 0, v45, s[38:39]
	flat_store_short v[46:47], v0 offset:1536
	v_add_co_u32_e64 v46, s[38:39], s15, v44
	v_cvt_pk_bf16_f32 v0, v82, v1
	s_nop 1
	v_addc_co_u32_e64 v47, s[38:39], 0, v45, s[38:39]
	flat_store_short v[46:47], v0
	v_add_co_u32_e64 v46, s[38:39], s24, v44
	v_cvt_pk_bf16_f32 v0, v83, v1
	s_nop 1
	v_addc_co_u32_e64 v47, s[38:39], 0, v45, s[38:39]
	flat_store_short v[46:47], v0 offset:512
	v_add_co_u32_e64 v46, s[38:39], s18, v44
	v_cvt_pk_bf16_f32 v0, v84, v1
	s_nop 1
	v_addc_co_u32_e64 v47, s[38:39], 0, v45, s[38:39]
	flat_store_short v[46:47], v0 offset:1024
	v_add_co_u32_e64 v46, s[38:39], s25, v44
	v_cvt_pk_bf16_f32 v0, v85, v1
	s_nop 1
	v_addc_co_u32_e64 v47, s[38:39], 0, v45, s[38:39]
; __device__ __forceinline__ unsigned cvt_pk_bf16(float lo, float hi) { unsigned r; asm volatile("v_cvt_pk_bf16_f32 %0, %1, %2" : "=v"(r) : "v"(lo), "v"(hi)); return r; }
; __device__ __forceinline__ bf16_t tobf(float f) { return (bf16_t)(cvt_pk_bf16(f, 0.f) & 0xffffu); }
; __device__ __forceinline__ void kvproj_task(int t, int l, const float* kvnorm, const float* kgain, const bf16_t* P, const bf16_t* WUKV, bf16_t* KB, bf16_t* VT, int fr, int fq) {
;     ...
;     for (int tb = 0; tb < 2; ++tb) { const int row = row0 + tb * 16, rr = isc ? row - ML : row;
;         const int b = isc ? rr >> 8 : rr >> 11, tpos = isc ? rr & 255 : rr & 2047, key = isc ? tpos : 256 + tpos;
;         float s2 = skr[tb];
; #pragma unroll
;         for (int cb = 0; cb < 4; ++cb) s2 += (acc[tb][cb][0] * acc[tb][cb][0] + acc[tb][cb][1] * acc[tb][cb][1]) + (acc[tb][cb][2] * acc[tb][cb][2] + acc[tb][cb][3] * acc[tb][cb][3]);
;         s2 += __shfl_xor(s2, 16); s2 += __shfl_xor(s2, 32);
;         const float rh = rsqrtf(s2 * (1.f / 96.f) + EPS);
;         bf16_t* kdst = KB + ((size_t)(b * 4 + h) * NKEY + key) * 96;
; #pragma unroll
;         for (int cb = 0; cb < 6; ++cb) { const f32x4 kg = *(const f32x4*)(kgain + l * 96 + cb * 16 + fq * 4); f32x4 v = (cb < 4 ? acc[tb][cb < 4 ? cb : 0] : kr[tb][cb >= 4 ? cb - 4 : 0]) * rh * kg;
;             if (cb >= 4) { const f32x4 rv = rope16(v, fq, (float)(cb == 4 ? (tpos >> 6) : (tpos & 63))); if (!isc) v = rv; }
;             u32x2 w; w.x = cvt_pk_bf16(v[0], v[1]); w.y = cvt_pk_bf16(v[2], v[3]);
;             *(u32x2*)(kdst + cb * 16 + fq * 4) = w; }
; #pragma unroll
;         for (int cb = 4; cb < 8; ++cb)
; #pragma unroll
;             for (int q = 0; q < 4; ++q) VT[((size_t)(b * 4 + h) * 64 + (cb - 4) * 16 + fq * 4 + q) * NKEY + key] = tobf(acc[tb][cb][q]); }
	flat_store_short v[46:47], v0 offset:1536
	v_add_co_u32_e64 v46, s[38:39], s26, v44
	v_cvt_pk_bf16_f32 v0, v90, v1
	s_nop 1
	v_addc_co_u32_e64 v47, s[38:39], 0, v45, s[38:39]
	flat_store_short v[46:47], v0
	v_add_co_u32_e64 v46, s[38:39], s27, v44
	v_cvt_pk_bf16_f32 v0, v91, v1
	s_nop 1
	v_addc_co_u32_e64 v47, s[38:39], 0, v45, s[38:39]
	flat_store_short v[46:47], v0 offset:512
	v_add_co_u32_e64 v46, s[38:39], s44, v44
	v_cvt_pk_bf16_f32 v0, v92, v1
	s_nop 1
	v_addc_co_u32_e64 v47, s[38:39], 0, v45, s[38:39]
	flat_store_short v[46:47], v0 offset:1024
	v_add_co_u32_e64 v46, s[38:39], s45, v44
	v_cvt_pk_bf16_f32 v0, v93, v1
	s_nop 1
	v_addc_co_u32_e64 v47, s[38:39], 0, v45, s[38:39]
	flat_store_short v[46:47], v0 offset:1536
	v_add_co_u32_e64 v46, s[38:39], s46, v44
	v_cvt_pk_bf16_f32 v0, v38, v1
	s_nop 1
	v_addc_co_u32_e64 v47, s[38:39], 0, v45, s[38:39]
	v_add_co_u32_e64 v38, s[38:39], s48, v44
	flat_store_short v[46:47], v0
	v_cvt_pk_bf16_f32 v0, v39, v1
	s_nop 0
	v_addc_co_u32_e64 v39, s[38:39], 0, v45, s[38:39]
	flat_store_short v[38:39], v0 offset:512
	v_add_co_u32_e64 v38, s[38:39], s51, v44
	v_cvt_pk_bf16_f32 v0, v40, v1
	v_pk_add_f32 v[46:47], v[192:193], v[192:193] op_sel:[0,1] op_sel_hi:[1,0]
	s_nop 0
	v_addc_co_u32_e64 v39, s[38:39], 0, v45, s[38:39]
	flat_store_short v[38:39], v0 offset:1024
	v_add_co_u32_e64 v38, s[38:39], s52, v44
	v_cvt_pk_bf16_f32 v0, v41, v1
	s_nop 1
	v_addc_co_u32_e64 v39, s[38:39], 0, v45, s[38:39]
	flat_store_short v[38:39], v0 offset:1536
	v_add_u32_e32 v0, 0xffffc010, v171
	v_cndmask_b32_e32 v39, v173, v0, vcc
	v_mul_f32_e32 v0, v4, v4
	v_mov_b32_e32 v47, v0
	v_mul_f32_e32 v0, v179, v179
	v_and_b32_e32 v44, v39, v43
	v_mul_f32_e32 v43, v5, v5
	v_mov_b32_e32 v173, v3
	v_pk_fma_f32 v[48:49], v[178:179], v[178:179], v[0:1] op_sel_hi:[1,1,0]
	v_mov_b32_e32 v171, v2
	v_pk_mul_f32 v[40:41], v[172:173], v[172:173]
	v_mov_b32_e32 v49, v43
	v_pk_fma_f32 v[40:41], v[170:171], v[170:171], v[40:41]
	v_pk_add_f32 v[46:47], v[46:47], v[48:49]
	v_pk_mul_f32 v[48:49], v[6:7], v[6:7]
	v_pk_add_f32 v[40:41], v[40:41], v[46:47]
	v_pk_mul_f32 v[46:47], v[8:9], v[8:9]
	v_mul_f32_e32 v0, v26, v26
	v_pk_mov_b32 v[50:51], v[48:49], v[46:47] op_sel:[1,0]
	v_mov_b32_e32 v49, v47
	v_pk_add_f32 v[46:47], v[50:51], v[48:49]
	v_mul_f32_e32 v43, v27, v27
	v_pk_add_f32 v[40:41], v[40:41], v[40:41] op_sel:[0,1] op_sel_hi:[1,0]
	v_pk_add_f32 v[46:47], v[46:47], v[46:47] op_sel:[0,1] op_sel_hi:[1,0]
	v_mov_b32_e32 v41, v0
	v_mov_b32_e32 v47, v43
	v_mul_f32_e32 v0, v19, v19
	v_pk_add_f32 v[40:41], v[40:41], v[46:47]
	v_pk_fma_f32 v[46:47], v[18:19], v[18:19], v[0:1] op_sel_hi:[1,1,0]
	v_mul_f32_e32 v0, v21, v21
	v_mul_f32_e32 v45, v28, v28
	v_mul_f32_e32 v50, v29, v29
	v_pk_fma_f32 v[48:49], v[20:21], v[20:21], v[0:1] op_sel_hi:[1,1,0]
	v_mov_b32_e32 v47, v45
	v_mov_b32_e32 v49, v50
	v_pk_add_f32 v[46:47], v[46:47], v[48:49]
	v_add_u32_e32 v38, 0x100, v44
	v_pk_add_f32 v[40:41], v[40:41], v[46:47]
	v_cndmask_b32_e32 v0, v38, v44, vcc
	v_add_f32_e32 v40, v40, v41
	ds_bpermute_b32 v38, v215, v40
	v_ashrrev_i32_e32 v41, v42, v39
	v_lshrrev_b32_e32 v44, 6, v44
	v_mov_b32_e32 v171, v172
	s_waitcnt lgkmcnt(0)
	v_add_f32_e32 v38, v40, v38
	ds_bpermute_b32 v40, v216, v38
	s_waitcnt lgkmcnt(0)
	v_add_f32_e32 v38, v38, v40
	v_fmamk_f32 v38, v38, 0x3c2aaaab, v197
	v_cmp_gt_f32_e64 s[38:39], s47, v38
	v_mul_f32_e32 v40, 0x4b800000, v38
	s_nop 0
	v_cndmask_b32_e64 v38, v38, v40, s[38:39]
	v_rsq_f32_e32 v38, v38
	s_nop 0
	v_mul_f32_e32 v40, 0x45800000, v38
	v_cndmask_b32_e64 v38, v38, v40, s[38:39]
	v_lshl_or_b32 v40, v41, 2, s22
	v_mad_i64_i32 v[46:47], s[6:7], v40, s9, v[0:1]
	v_mad_u64_u32 v[42:43], s[6:7], v46, s14, v[102:103]
	v_mad_i32_i24 v43, v47, s14, v43
	global_load_dwordx4 v[46:49], v[100:101], off
	v_pk_mul_f32 v[2:3], v[2:3], v[38:39] op_sel_hi:[1,0]
	v_pk_mul_f32 v[4:5], v[4:5], v[38:39] op_sel_hi:[1,0]
	v_pk_mul_f32 v[6:7], v[6:7], v[38:39] op_sel_hi:[1,0]
	v_pk_mul_f32 v[8:9], v[8:9], v[38:39] op_sel_hi:[1,0]
	v_ashrrev_i32_e32 v41, 31, v40
	v_lshlrev_b32_e32 v0, 1, v0
	s_waitcnt vmcnt(0)
	v_pk_mul_f32 v[2:3], v[46:47], v[2:3]
	v_pk_mul_f32 v[4:5], v[48:49], v[4:5]
	v_cvt_pk_bf16_f32 v2, v2, v3
	s_nop 0
	v_cvt_pk_bf16_f32 v3, v4, v5
	flat_store_dwordx2 v[42:43], v[2:3]
	global_load_dwordx4 v[2:5], v[100:101], off offset:64
	s_waitcnt vmcnt(0)
	v_pk_mul_f32 v[2:3], v[2:3], v[6:7]
	v_pk_mul_f32 v[4:5], v[4:5], v[8:9]
	v_cvt_pk_bf16_f32 v2, v2, v3
	v_pk_mul_f32 v[8:9], v[18:19], v[38:39] op_sel_hi:[1,0]
	v_cvt_pk_bf16_f32 v3, v4, v5
	flat_store_dwordx2 v[42:43], v[2:3] offset:32
	global_load_dwordx4 v[2:5], v[100:101], off offset:128
	v_pk_mul_f32 v[6:7], v[20:21], v[38:39] op_sel_hi:[1,0]
	s_waitcnt vmcnt(0)
	v_pk_mul_f32 v[2:3], v[2:3], v[8:9]
	v_pk_mul_f32 v[4:5], v[4:5], v[6:7]
	v_cvt_pk_bf16_f32 v2, v2, v3
	v_pk_mul_f32 v[8:9], v[26:27], v[38:39] op_sel_hi:[1,0]
	v_cvt_pk_bf16_f32 v3, v4, v5
	flat_store_dwordx2 v[42:43], v[2:3] offset:64
	global_load_dwordx4 v[2:5], v[100:101], off offset:192
	v_pk_mul_f32 v[6:7], v[28:29], v[38:39] op_sel_hi:[1,0]
	v_cvt_f32_ubyte0_e32 v27, v44
	v_mul_f32_e32 v18, v217, v27
	v_mul_f32_e32 v19, 0.15915494, v18
	v_cos_f32_e32 v18, v19
	v_sin_f32_e32 v20, v19
	v_mul_f32_e32 v19, v218, v27
	v_mul_f32_e32 v21, 0.15915494, v19
	v_cos_f32_e32 v19, v21
	v_sin_f32_e32 v21, v21
	s_waitcnt vmcnt(0)
; __device__ __forceinline__ unsigned cvt_pk_bf16(float lo, float hi) { unsigned r; asm volatile("v_cvt_pk_bf16_f32 %0, %1, %2" : "=v"(r) : "v"(lo), "v"(hi)); return r; }
; __device__ __forceinline__ bf16_t tobf(float f) { return (bf16_t)(cvt_pk_bf16(f, 0.f) & 0xffffu); }
; __device__ __forceinline__ f32x4 rope16(f32x4 v, int fq, float pos) {
;     f32x4 pr; pr[0] = __shfl_xor(v[0], 32); pr[1] = __shfl_xor(v[1], 32); pr[2] = __shfl_xor(v[2], 32); pr[3] = __shfl_xor(v[3], 32);
;     f32x4 o;
; #pragma unroll
;     for (int q = 0; q < 4; ++q) { const int f = (fq * 4 + q) & 7; const float inv = __builtin_amdgcn_exp2f(-(float)f * 1.6609640474f); float sn, cs; __sincosf(pos * inv, &sn, &cs);
;         o[q] = fq < 2 ? v[q] * cs - pr[q] * sn : pr[q] * sn + v[q] * cs; }
;     return o;
; }
; __device__ __forceinline__ void kvproj_task(int t, int l, const float* kvnorm, const float* kgain, const bf16_t* P, const bf16_t* WUKV, bf16_t* KB, bf16_t* VT, int fr, int fq) {
;     ...
;     for (int tb = 0; tb < 2; ++tb) { const int row = row0 + tb * 16, rr = isc ? row - ML : row;
;         const int b = isc ? rr >> 8 : rr >> 11, tpos = isc ? rr & 255 : rr & 2047, key = isc ? tpos : 256 + tpos;
;         float s2 = skr[tb];
; #pragma unroll
;         for (int cb = 0; cb < 4; ++cb) s2 += (acc[tb][cb][0] * acc[tb][cb][0] + acc[tb][cb][1] * acc[tb][cb][1]) + (acc[tb][cb][2] * acc[tb][cb][2] + acc[tb][cb][3] * acc[tb][cb][3]);
;         s2 += __shfl_xor(s2, 16); s2 += __shfl_xor(s2, 32);
;         const float rh = rsqrtf(s2 * (1.f / 96.f) + EPS);
;         bf16_t* kdst = KB + ((size_t)(b * 4 + h) * NKEY + key) * 96;
; #pragma unroll
;         for (int cb = 0; cb < 6; ++cb) { const f32x4 kg = *(const f32x4*)(kgain + l * 96 + cb * 16 + fq * 4); f32x4 v = (cb < 4 ? acc[tb][cb < 4 ? cb : 0] : kr[tb][cb >= 4 ? cb - 4 : 0]) * rh * kg;
;             if (cb >= 4) { const f32x4 rv = rope16(v, fq, (float)(cb == 4 ? (tpos >> 6) : (tpos & 63))); if (!isc) v = rv; }
;             u32x2 w; w.x = cvt_pk_bf16(v[0], v[1]); w.y = cvt_pk_bf16(v[2], v[3]);
;             *(u32x2*)(kdst + cb * 16 + fq * 4) = w; }
; #pragma unroll
;         for (int cb = 4; cb < 8; ++cb)
; #pragma unroll
;             for (int q = 0; q < 4; ++q) VT[((size_t)(b * 4 + h) * 64 + (cb - 4) * 16 + fq * 4 + q) * NKEY + key] = tobf(acc[tb][cb][q]); }
	v_pk_mul_f32 v[2:3], v[8:9], v[2:3]
	v_pk_mul_f32 v[4:5], v[6:7], v[4:5]
	v_cvt_pk_bf16_f32 v2, v2, v3
	v_mov_b32_e32 v6, v180
	v_cvt_pk_bf16_f32 v3, v4, v5
	flat_store_dwordx2 v[42:43], v[2:3] offset:96
	global_load_dwordx4 v[2:5], v[100:101], off offset:256
	v_mov_b32_e32 v7, v182
	v_pk_mul_f32 v[6:7], v[38:39], v[6:7] op_sel_hi:[0,1]
	v_mov_b32_e32 v182, v181
	v_pk_mul_f32 v[8:9], v[38:39], v[182:183] op_sel_hi:[0,1]
	s_waitcnt vmcnt(0)
	v_pk_mul_f32 v[2:3], v[6:7], v[2:3]
	ds_bpermute_b32 v6, v216, v2
	ds_bpermute_b32 v7, v216, v3
	v_pk_mul_f32 v[4:5], v[8:9], v[4:5]
	ds_bpermute_b32 v8, v216, v4
	ds_bpermute_b32 v9, v216, v5
	s_waitcnt lgkmcnt(0)
	v_pk_mul_f32 v[6:7], v[20:21], v[6:7]
	v_mul_f32_e32 v20, v219, v27
	v_mul_f32_e32 v21, 0.15915494, v20
	v_cos_f32_e32 v20, v21
	v_sin_f32_e32 v26, v21
	v_mul_f32_e32 v21, v220, v27
	v_mul_f32_e32 v27, 0.15915494, v21
	v_cos_f32_e32 v21, v27
	v_sin_f32_e32 v27, v27
	v_cndmask_b32_e64 v7, v7, -v7, s[36:37]
	v_cndmask_b32_e64 v6, v6, -v6, s[36:37]
	v_pk_fma_f32 v[6:7], v[18:19], v[2:3], v[6:7]
	v_pk_mul_f32 v[8:9], v[26:27], v[8:9]
	v_cndmask_b32_e32 v2, v6, v2, vcc
	v_cndmask_b32_e64 v9, v9, -v9, s[36:37]
	v_cndmask_b32_e64 v8, v8, -v8, s[36:37]
	v_pk_fma_f32 v[8:9], v[20:21], v[4:5], v[8:9]
	v_cndmask_b32_e32 v3, v7, v3, vcc
	v_cndmask_b32_e32 v4, v8, v4, vcc
	v_cndmask_b32_e32 v5, v9, v5, vcc
	v_cvt_pk_bf16_f32 v2, v2, v3
	v_cvt_pk_bf16_f32 v3, v4, v5
	flat_store_dwordx2 v[42:43], v[2:3] offset:128
	global_load_dwordx4 v[2:5], v[100:101], off offset:320
	v_and_b32_e32 v18, 63, v39
	v_cvt_f32_ubyte0_e32 v27, v18
	v_mul_f32_e32 v18, v217, v27
	v_pk_mul_f32 v[6:7], v[38:39], v[178:179] op_sel_hi:[0,1]
	v_mul_f32_e32 v19, 0.15915494, v18
	v_cos_f32_e32 v18, v19
	v_sin_f32_e32 v20, v19
	v_mul_f32_e32 v19, v218, v27
	v_mul_f32_e32 v21, 0.15915494, v19
	v_cos_f32_e32 v19, v21
	v_sin_f32_e32 v21, v21
	v_pk_mul_f32 v[8:9], v[38:39], v[170:171] op_sel_hi:[0,1]
	s_waitcnt vmcnt(0)
	v_pk_mul_f32 v[2:3], v[6:7], v[2:3]
	ds_bpermute_b32 v6, v216, v2
	ds_bpermute_b32 v7, v216, v3
	v_pk_mul_f32 v[4:5], v[8:9], v[4:5]
	ds_bpermute_b32 v8, v216, v4
	ds_bpermute_b32 v9, v216, v5
	s_waitcnt lgkmcnt(0)
	v_pk_mul_f32 v[6:7], v[20:21], v[6:7]
	v_mul_f32_e32 v20, v219, v27
	v_mul_f32_e32 v21, 0.15915494, v20
	v_cos_f32_e32 v20, v21
	v_sin_f32_e32 v26, v21
	v_mul_f32_e32 v21, v220, v27
	v_mul_f32_e32 v27, 0.15915494, v21
	v_cos_f32_e32 v21, v27
	v_sin_f32_e32 v27, v27
	v_cndmask_b32_e64 v7, v7, -v7, s[36:37]
	v_cndmask_b32_e64 v6, v6, -v6, s[36:37]
	v_pk_fma_f32 v[6:7], v[18:19], v[2:3], v[6:7]
	v_pk_mul_f32 v[8:9], v[26:27], v[8:9]
	v_cndmask_b32_e32 v2, v6, v2, vcc
	v_cndmask_b32_e64 v9, v9, -v9, s[36:37]
	v_cndmask_b32_e64 v8, v8, -v8, s[36:37]
	v_pk_fma_f32 v[8:9], v[20:21], v[4:5], v[8:9]
	v_cndmask_b32_e32 v3, v7, v3, vcc
	v_cndmask_b32_e32 v4, v8, v4, vcc
	v_cndmask_b32_e32 v5, v9, v5, vcc
	v_cvt_pk_bf16_f32 v2, v2, v3
	v_cvt_pk_bf16_f32 v3, v4, v5
	v_lshlrev_b64 v[4:5], 6, v[40:41]
	flat_store_dwordx2 v[42:43], v[2:3] offset:160
	v_lshl_add_u64 v[2:3], s[40:41], 0, v[0:1]
	v_or_b32_e32 v0, v4, v96
	v_mad_u64_u32 v[2:3], s[6:7], v0, s88, v[2:3]
	v_cvt_pk_bf16_f32 v4, v14, v1
	v_mad_i32_i24 v3, v5, s88, v3
	flat_store_short v[2:3], v4
	v_add_co_u32_e32 v4, vcc, s19, v2
	v_cvt_pk_bf16_f32 v0, v15, v1
	s_nop 1
	v_addc_co_u32_e32 v5, vcc, 0, v3, vcc
	flat_store_short v[4:5], v0 offset:512
	v_add_co_u32_e32 v4, vcc, s33, v2
	v_cvt_pk_bf16_f32 v0, v16, v1
	s_nop 1
	v_addc_co_u32_e32 v5, vcc, 0, v3, vcc
	flat_store_short v[4:5], v0 offset:1024
	v_add_co_u32_e32 v4, vcc, s23, v2
	v_cvt_pk_bf16_f32 v0, v17, v1
	s_nop 1
	v_addc_co_u32_e32 v5, vcc, 0, v3, vcc
	flat_store_short v[4:5], v0 offset:1536
	v_add_co_u32_e32 v4, vcc, s15, v2
	v_cvt_pk_bf16_f32 v0, v22, v1
	s_nop 1
	v_addc_co_u32_e32 v5, vcc, 0, v3, vcc
	flat_store_short v[4:5], v0
	v_add_co_u32_e32 v4, vcc, s24, v2
	v_cvt_pk_bf16_f32 v0, v23, v1
	s_nop 1
	v_addc_co_u32_e32 v5, vcc, 0, v3, vcc
	flat_store_short v[4:5], v0 offset:512
	v_add_co_u32_e32 v4, vcc, s18, v2
	v_cvt_pk_bf16_f32 v0, v24, v1
	s_nop 1
	v_addc_co_u32_e32 v5, vcc, 0, v3, vcc
	flat_store_short v[4:5], v0 offset:1024
	v_add_co_u32_e32 v4, vcc, s25, v2
	v_cvt_pk_bf16_f32 v0, v25, v1
	s_nop 1
	v_addc_co_u32_e32 v5, vcc, 0, v3, vcc
	flat_store_short v[4:5], v0 offset:1536
	v_add_co_u32_e32 v4, vcc, s26, v2
	v_cvt_pk_bf16_f32 v0, v30, v1
	s_nop 1
	v_addc_co_u32_e32 v5, vcc, 0, v3, vcc
	flat_store_short v[4:5], v0
	v_add_co_u32_e32 v4, vcc, s27, v2
	v_cvt_pk_bf16_f32 v0, v31, v1
	s_nop 1
	v_addc_co_u32_e32 v5, vcc, 0, v3, vcc
	flat_store_short v[4:5], v0 offset:512
	v_add_co_u32_e32 v4, vcc, s44, v2
	v_cvt_pk_bf16_f32 v0, v32, v1
	s_nop 1
	v_addc_co_u32_e32 v5, vcc, 0, v3, vcc
	flat_store_short v[4:5], v0 offset:1024
	v_add_co_u32_e32 v4, vcc, s45, v2
	v_cvt_pk_bf16_f32 v0, v33, v1
	s_nop 1
	v_addc_co_u32_e32 v5, vcc, 0, v3, vcc
	flat_store_short v[4:5], v0 offset:1536
	v_add_co_u32_e32 v4, vcc, s46, v2
	v_cvt_pk_bf16_f32 v0, v34, v1
	s_nop 1
	v_addc_co_u32_e32 v5, vcc, 0, v3, vcc
	flat_store_short v[4:5], v0
	v_add_co_u32_e32 v4, vcc, s48, v2
	v_cvt_pk_bf16_f32 v0, v35, v1
	s_nop 1
	v_addc_co_u32_e32 v5, vcc, 0, v3, vcc
	flat_store_short v[4:5], v0 offset:512
	v_add_co_u32_e32 v4, vcc, 0x38000, v2
	v_cvt_pk_bf16_f32 v0, v36, v1
	s_nop 1
	v_addc_co_u32_e32 v5, vcc, 0, v3, vcc
	v_add_co_u32_e32 v2, vcc, 0x39000, v2
	flat_store_short v[4:5], v0 offset:1024
	s_nop 0
	v_addc_co_u32_e32 v3, vcc, 0, v3, vcc
	v_cvt_pk_bf16_f32 v0, v37, v1
	flat_store_short v[2:3], v0 offset:1536
	s_cbranch_scc0 .LBB0_422
